# GEMM K-loops: A tile of step k+2 issued in the LDS-quiet MFMA groups before the barrier (B stays in the first two groups)
# speedup vs baseline: 1.0322x; 1.0322x over previous
.Lg161_loop:
	s_add_u32 s51, s50, 0x10000
	s_sub_u32 s53, s51, 0x28000
	s_cmp_ge_u32 s51, 0x28000
	s_cselect_b32 s51, s53, s51
	s_add_u32 s52, s49, 0x20000
	s_sub_u32 s53, s52, 0x28000
	s_cmp_ge_u32 s52, 0x28000
	s_cselect_b32 s52, s53, s52
	v_add_u32_e32 v137, s50, v135
	s_waitcnt lgkmcnt(4)
	s_waitcnt lgkmcnt(3)
	v_mfma_f32_16x16x32_bf16 v[112:115], v[164:167], v[224:227], v[112:115]
	v_mfma_f32_16x16x32_bf16 v[120:123], v[168:171], v[224:227], v[120:123]
	v_mfma_f32_16x16x32_bf16 v[96:99], v[172:175], v[224:227], v[96:99]
	v_mfma_f32_16x16x32_bf16 v[104:107], v[176:179], v[224:227], v[104:107]
	s_add_u32 m0, s51, s48
	s_nop 0
	global_load_lds_dwordx4 v139, s[64:65]
	s_add_u32 s64, s64, 0x80
	s_addc_u32 s65, s65, 0
	s_add_u32 s53, s51, s48
	s_add_u32 m0, s53, 0x2000
	s_nop 0
	global_load_lds_dwordx4 v139, s[66:67]
	s_add_u32 s66, s66, 0x80
	s_addc_u32 s67, s67, 0
	ds_read_b128 v[224:227], v136 offset:8192
	ds_read_b128 v[180:183], v137
	s_waitcnt lgkmcnt(4)
	v_mfma_f32_16x16x32_bf16 v[116:119], v[164:167], v[228:231], v[116:119]
	v_mfma_f32_16x16x32_bf16 v[124:127], v[168:171], v[228:231], v[124:127]
	v_mfma_f32_16x16x32_bf16 v[100:103], v[172:175], v[228:231], v[100:103]
	v_mfma_f32_16x16x32_bf16 v[108:111], v[176:179], v[228:231], v[108:111]
	s_add_u32 s53, s51, s48
	s_add_u32 m0, s53, 0x4000
	s_nop 0
	global_load_lds_dwordx4 v139, s[68:69]
	s_add_u32 s68, s68, 0x80
	s_addc_u32 s69, s69, 0
	s_add_u32 s53, s51, s48
	s_add_u32 m0, s53, 0x6000
	s_nop 0
	global_load_lds_dwordx4 v139, s[70:71]
	s_add_u32 s70, s70, 0x80
	s_addc_u32 s71, s71, 0
	ds_read_b128 v[228:231], v136 offset:10240
	ds_read_b128 v[212:215], v137 offset:2048
	s_waitcnt lgkmcnt(5)
	v_mfma_f32_16x16x32_bf16 v[80:83], v[164:167], v[232:235], v[80:83]
	v_mfma_f32_16x16x32_bf16 v[88:91], v[168:171], v[232:235], v[88:91]
	v_mfma_f32_16x16x32_bf16 v[64:67], v[172:175], v[232:235], v[64:67]
	v_mfma_f32_16x16x32_bf16 v[72:75], v[176:179], v[232:235], v[72:75]
	ds_read_b128 v[232:235], v136 offset:12288
	ds_read_b128 v[216:219], v137 offset:4096
	s_waitcnt lgkmcnt(6)
	v_mfma_f32_16x16x32_bf16 v[84:87], v[164:167], v[236:239], v[84:87]
	v_mfma_f32_16x16x32_bf16 v[92:95], v[168:171], v[236:239], v[92:95]
	v_mfma_f32_16x16x32_bf16 v[68:71], v[172:175], v[236:239], v[68:71]
	v_mfma_f32_16x16x32_bf16 v[76:79], v[176:179], v[236:239], v[76:79]
	ds_read_b128 v[236:239], v136 offset:14336
	ds_read_b128 v[220:223], v137 offset:6144
	v_add_u32_e32 v136, s49, v133
	s_waitcnt lgkmcnt(7)
	v_mfma_f32_16x16x32_bf16 v[48:51], v[164:167], v[224:227], v[48:51]
	v_mfma_f32_16x16x32_bf16 v[56:59], v[168:171], v[224:227], v[56:59]
	v_mfma_f32_16x16x32_bf16 v[32:35], v[172:175], v[224:227], v[32:35]
	v_mfma_f32_16x16x32_bf16 v[40:43], v[176:179], v[224:227], v[40:43]
	ds_read_b128 v[224:227], v136
	s_waitcnt lgkmcnt(6)
	v_mfma_f32_16x16x32_bf16 v[52:55], v[164:167], v[228:231], v[52:55]
	v_mfma_f32_16x16x32_bf16 v[60:63], v[168:171], v[228:231], v[60:63]
	v_mfma_f32_16x16x32_bf16 v[36:39], v[172:175], v[228:231], v[36:39]
	v_mfma_f32_16x16x32_bf16 v[44:47], v[176:179], v[228:231], v[44:47]
	ds_read_b128 v[228:231], v136 offset:2048
	s_waitcnt lgkmcnt(5)
	v_mfma_f32_16x16x32_bf16 v[16:19], v[164:167], v[232:235], v[16:19]
	v_mfma_f32_16x16x32_bf16 v[24:27], v[168:171], v[232:235], v[24:27]
	v_mfma_f32_16x16x32_bf16 v[0:3], v[172:175], v[232:235], v[0:3]
	v_mfma_f32_16x16x32_bf16 v[8:11], v[176:179], v[232:235], v[8:11]
	ds_read_b128 v[232:235], v136 offset:4096
	s_waitcnt lgkmcnt(4)
	v_mfma_f32_16x16x32_bf16 v[20:23], v[164:167], v[236:239], v[20:23]
	v_mfma_f32_16x16x32_bf16 v[28:31], v[168:171], v[236:239], v[28:31]
	v_mfma_f32_16x16x32_bf16 v[4:7], v[172:175], v[236:239], v[4:7]
	v_mfma_f32_16x16x32_bf16 v[12:15], v[176:179], v[236:239], v[12:15]
	ds_read_b128 v[236:239], v136 offset:6144
	s_waitcnt lgkmcnt(4)
	s_waitcnt lgkmcnt(3)
	v_mfma_f32_16x16x32_bf16 v[112:115], v[180:183], v[224:227], v[112:115]
	v_mfma_f32_16x16x32_bf16 v[120:123], v[212:215], v[224:227], v[120:123]
	v_mfma_f32_16x16x32_bf16 v[96:99], v[216:219], v[224:227], v[96:99]
	v_mfma_f32_16x16x32_bf16 v[104:107], v[220:223], v[224:227], v[104:107]
	ds_read_b128 v[224:227], v136 offset:8192
	s_waitcnt lgkmcnt(3)
	v_mfma_f32_16x16x32_bf16 v[116:119], v[180:183], v[228:231], v[116:119]
	v_mfma_f32_16x16x32_bf16 v[124:127], v[212:215], v[228:231], v[124:127]
	v_mfma_f32_16x16x32_bf16 v[100:103], v[216:219], v[228:231], v[100:103]
	v_mfma_f32_16x16x32_bf16 v[108:111], v[220:223], v[228:231], v[108:111]
	ds_read_b128 v[228:231], v136 offset:10240
	s_waitcnt lgkmcnt(3)
	v_mfma_f32_16x16x32_bf16 v[80:83], v[180:183], v[232:235], v[80:83]
	v_mfma_f32_16x16x32_bf16 v[88:91], v[212:215], v[232:235], v[88:91]
	v_mfma_f32_16x16x32_bf16 v[64:67], v[216:219], v[232:235], v[64:67]
	v_mfma_f32_16x16x32_bf16 v[72:75], v[220:223], v[232:235], v[72:75]
	ds_read_b128 v[232:235], v136 offset:12288
	s_waitcnt lgkmcnt(3)
	v_mfma_f32_16x16x32_bf16 v[84:87], v[180:183], v[236:239], v[84:87]
	v_mfma_f32_16x16x32_bf16 v[92:95], v[212:215], v[236:239], v[92:95]
	v_mfma_f32_16x16x32_bf16 v[68:71], v[216:219], v[236:239], v[68:71]
	v_mfma_f32_16x16x32_bf16 v[76:79], v[220:223], v[236:239], v[76:79]
	ds_read_b128 v[236:239], v136 offset:14336
	s_waitcnt lgkmcnt(3)
	v_mfma_f32_16x16x32_bf16 v[48:51], v[180:183], v[224:227], v[48:51]
	v_mfma_f32_16x16x32_bf16 v[56:59], v[212:215], v[224:227], v[56:59]
	v_mfma_f32_16x16x32_bf16 v[32:35], v[216:219], v[224:227], v[32:35]
	v_mfma_f32_16x16x32_bf16 v[40:43], v[220:223], v[224:227], v[40:43]
	s_add_u32 m0, s52, s48
	s_nop 0
	global_load_lds_dwordx4 v138, s[56:57]
	s_add_u32 s56, s56, 0x80
	s_addc_u32 s57, s57, 0
	s_add_u32 s53, s52, s48
	s_add_u32 m0, s53, 0x2000
	s_nop 0
	global_load_lds_dwordx4 v138, s[58:59]
	s_add_u32 s58, s58, 0x80
	s_addc_u32 s59, s59, 0
	s_waitcnt lgkmcnt(2)
	v_mfma_f32_16x16x32_bf16 v[52:55], v[180:183], v[228:231], v[52:55]
	v_mfma_f32_16x16x32_bf16 v[60:63], v[212:215], v[228:231], v[60:63]
	v_mfma_f32_16x16x32_bf16 v[36:39], v[216:219], v[228:231], v[36:39]
	v_mfma_f32_16x16x32_bf16 v[44:47], v[220:223], v[228:231], v[44:47]
	s_add_u32 s53, s52, s48
	s_add_u32 m0, s53, 0x4000
	s_nop 0
	global_load_lds_dwordx4 v138, s[60:61]
	s_add_u32 s60, s60, 0x80
	s_addc_u32 s61, s61, 0
	s_add_u32 s53, s52, s48
	s_add_u32 m0, s53, 0x6000
	s_nop 0
	global_load_lds_dwordx4 v138, s[62:63]
	s_add_u32 s62, s62, 0x80
	s_addc_u32 s63, s63, 0
	s_waitcnt lgkmcnt(1)
	v_mfma_f32_16x16x32_bf16 v[16:19], v[180:183], v[232:235], v[16:19]
	v_mfma_f32_16x16x32_bf16 v[24:27], v[212:215], v[232:235], v[24:27]
	v_mfma_f32_16x16x32_bf16 v[0:3], v[216:219], v[232:235], v[0:3]
	v_mfma_f32_16x16x32_bf16 v[8:11], v[220:223], v[232:235], v[8:11]
	s_waitcnt lgkmcnt(0)
	s_add_u32 s4, s4, 0x80
	s_addc_u32 s5, s5, 0
	s_add_u32 s49, s49, 0x10000
	s_sub_u32 s53, s49, 0x28000
	s_cmp_ge_u32 s49, 0x28000
	s_cselect_b32 s49, s53, s49
	s_mov_b32 s50, s51
	s_waitcnt vmcnt(4)
	s_barrier
	v_add_u32_e32 v137, s50, v134
	v_add_u32_e32 v136, s49, v132
	ds_read_b128 v[164:167], v137
	ds_read_b128 v[168:171], v137 offset:2048
	ds_read_b128 v[172:175], v137 offset:4096
	ds_read_b128 v[176:179], v137 offset:6144
	ds_read_b128 v[224:227], v136
	ds_read_b128 v[228:231], v136 offset:2048
	ds_read_b128 v[232:235], v136 offset:4096
	v_mfma_f32_16x16x32_bf16 v[20:23], v[180:183], v[236:239], v[20:23]
	v_mfma_f32_16x16x32_bf16 v[28:31], v[212:215], v[236:239], v[28:31]
	v_mfma_f32_16x16x32_bf16 v[4:7], v[216:219], v[236:239], v[4:7]
	v_mfma_f32_16x16x32_bf16 v[12:15], v[220:223], v[236:239], v[12:15]
	ds_read_b128 v[236:239], v136 offset:6144
	s_cmpk_lg_i32 s4, 0xf00
	s_cbranch_scc1 .Lg161_loop
	s_add_u32 s51, s50, 0x10000
	s_sub_u32 s53, s51, 0x28000
	s_cmp_ge_u32 s51, 0x28000
	s_cselect_b32 s51, s53, s51
	v_add_u32_e32 v137, s50, v135
	s_waitcnt lgkmcnt(4)
	s_waitcnt lgkmcnt(3)
	v_mfma_f32_16x16x32_bf16 v[112:115], v[164:167], v[224:227], v[112:115]
	v_mfma_f32_16x16x32_bf16 v[120:123], v[168:171], v[224:227], v[120:123]
	v_mfma_f32_16x16x32_bf16 v[96:99], v[172:175], v[224:227], v[96:99]
	v_mfma_f32_16x16x32_bf16 v[104:107], v[176:179], v[224:227], v[104:107]
	s_add_u32 m0, s51, s48
	s_nop 0
	global_load_lds_dwordx4 v139, s[64:65]
	s_add_u32 s64, s64, 0x80
	s_addc_u32 s65, s65, 0
	s_add_u32 s53, s51, s48
	s_add_u32 m0, s53, 0x2000
	s_nop 0
	global_load_lds_dwordx4 v139, s[66:67]
	s_add_u32 s66, s66, 0x80
	s_addc_u32 s67, s67, 0
	ds_read_b128 v[224:227], v136 offset:8192
	ds_read_b128 v[180:183], v137
	s_waitcnt lgkmcnt(4)
	v_mfma_f32_16x16x32_bf16 v[116:119], v[164:167], v[228:231], v[116:119]
	v_mfma_f32_16x16x32_bf16 v[124:127], v[168:171], v[228:231], v[124:127]
	v_mfma_f32_16x16x32_bf16 v[100:103], v[172:175], v[228:231], v[100:103]
	v_mfma_f32_16x16x32_bf16 v[108:111], v[176:179], v[228:231], v[108:111]
	s_add_u32 s53, s51, s48
	s_add_u32 m0, s53, 0x4000
	s_nop 0
	global_load_lds_dwordx4 v139, s[68:69]
	s_add_u32 s68, s68, 0x80
	s_addc_u32 s69, s69, 0
	s_add_u32 s53, s51, s48
	s_add_u32 m0, s53, 0x6000
	s_nop 0
	global_load_lds_dwordx4 v139, s[70:71]
	s_add_u32 s70, s70, 0x80
	s_addc_u32 s71, s71, 0
	ds_read_b128 v[228:231], v136 offset:10240
	ds_read_b128 v[212:215], v137 offset:2048
	s_waitcnt lgkmcnt(5)
	v_mfma_f32_16x16x32_bf16 v[80:83], v[164:167], v[232:235], v[80:83]
	v_mfma_f32_16x16x32_bf16 v[88:91], v[168:171], v[232:235], v[88:91]
	v_mfma_f32_16x16x32_bf16 v[64:67], v[172:175], v[232:235], v[64:67]
	v_mfma_f32_16x16x32_bf16 v[72:75], v[176:179], v[232:235], v[72:75]
	ds_read_b128 v[232:235], v136 offset:12288
	ds_read_b128 v[216:219], v137 offset:4096
	s_waitcnt lgkmcnt(6)
	v_mfma_f32_16x16x32_bf16 v[84:87], v[164:167], v[236:239], v[84:87]
	v_mfma_f32_16x16x32_bf16 v[92:95], v[168:171], v[236:239], v[92:95]
	v_mfma_f32_16x16x32_bf16 v[68:71], v[172:175], v[236:239], v[68:71]
	v_mfma_f32_16x16x32_bf16 v[76:79], v[176:179], v[236:239], v[76:79]
	ds_read_b128 v[236:239], v136 offset:14336
	ds_read_b128 v[220:223], v137 offset:6144
	v_add_u32_e32 v136, s49, v133
	s_waitcnt lgkmcnt(7)
	v_mfma_f32_16x16x32_bf16 v[48:51], v[164:167], v[224:227], v[48:51]
	v_mfma_f32_16x16x32_bf16 v[56:59], v[168:171], v[224:227], v[56:59]
	v_mfma_f32_16x16x32_bf16 v[32:35], v[172:175], v[224:227], v[32:35]
	v_mfma_f32_16x16x32_bf16 v[40:43], v[176:179], v[224:227], v[40:43]
	ds_read_b128 v[224:227], v136
	s_waitcnt lgkmcnt(6)
	v_mfma_f32_16x16x32_bf16 v[52:55], v[164:167], v[228:231], v[52:55]
	v_mfma_f32_16x16x32_bf16 v[60:63], v[168:171], v[228:231], v[60:63]
	v_mfma_f32_16x16x32_bf16 v[36:39], v[172:175], v[228:231], v[36:39]
	v_mfma_f32_16x16x32_bf16 v[44:47], v[176:179], v[228:231], v[44:47]
	ds_read_b128 v[228:231], v136 offset:2048
	s_waitcnt lgkmcnt(5)
	v_mfma_f32_16x16x32_bf16 v[16:19], v[164:167], v[232:235], v[16:19]
	v_mfma_f32_16x16x32_bf16 v[24:27], v[168:171], v[232:235], v[24:27]
	v_mfma_f32_16x16x32_bf16 v[0:3], v[172:175], v[232:235], v[0:3]
	v_mfma_f32_16x16x32_bf16 v[8:11], v[176:179], v[232:235], v[8:11]
	ds_read_b128 v[232:235], v136 offset:4096
	s_waitcnt lgkmcnt(4)
	v_mfma_f32_16x16x32_bf16 v[20:23], v[164:167], v[236:239], v[20:23]
	v_mfma_f32_16x16x32_bf16 v[28:31], v[168:171], v[236:239], v[28:31]
	v_mfma_f32_16x16x32_bf16 v[4:7], v[172:175], v[236:239], v[4:7]
	v_mfma_f32_16x16x32_bf16 v[12:15], v[176:179], v[236:239], v[12:15]
	ds_read_b128 v[236:239], v136 offset:6144
	s_waitcnt lgkmcnt(4)
	s_waitcnt lgkmcnt(3)
	v_mfma_f32_16x16x32_bf16 v[112:115], v[180:183], v[224:227], v[112:115]
	v_mfma_f32_16x16x32_bf16 v[120:123], v[212:215], v[224:227], v[120:123]
	v_mfma_f32_16x16x32_bf16 v[96:99], v[216:219], v[224:227], v[96:99]
	v_mfma_f32_16x16x32_bf16 v[104:107], v[220:223], v[224:227], v[104:107]
	ds_read_b128 v[224:227], v136 offset:8192
	s_waitcnt lgkmcnt(3)
	v_mfma_f32_16x16x32_bf16 v[116:119], v[180:183], v[228:231], v[116:119]
	v_mfma_f32_16x16x32_bf16 v[124:127], v[212:215], v[228:231], v[124:127]
	v_mfma_f32_16x16x32_bf16 v[100:103], v[216:219], v[228:231], v[100:103]
	v_mfma_f32_16x16x32_bf16 v[108:111], v[220:223], v[228:231], v[108:111]
	ds_read_b128 v[228:231], v136 offset:10240
	s_waitcnt lgkmcnt(3)
	v_mfma_f32_16x16x32_bf16 v[80:83], v[180:183], v[232:235], v[80:83]
	v_mfma_f32_16x16x32_bf16 v[88:91], v[212:215], v[232:235], v[88:91]
	v_mfma_f32_16x16x32_bf16 v[64:67], v[216:219], v[232:235], v[64:67]
	v_mfma_f32_16x16x32_bf16 v[72:75], v[220:223], v[232:235], v[72:75]
	ds_read_b128 v[232:235], v136 offset:12288
	s_waitcnt lgkmcnt(3)
	v_mfma_f32_16x16x32_bf16 v[84:87], v[180:183], v[236:239], v[84:87]
	v_mfma_f32_16x16x32_bf16 v[92:95], v[212:215], v[236:239], v[92:95]
	v_mfma_f32_16x16x32_bf16 v[68:71], v[216:219], v[236:239], v[68:71]
	v_mfma_f32_16x16x32_bf16 v[76:79], v[220:223], v[236:239], v[76:79]
	ds_read_b128 v[236:239], v136 offset:14336
	s_waitcnt lgkmcnt(3)
	v_mfma_f32_16x16x32_bf16 v[48:51], v[180:183], v[224:227], v[48:51]
	v_mfma_f32_16x16x32_bf16 v[56:59], v[212:215], v[224:227], v[56:59]
	v_mfma_f32_16x16x32_bf16 v[32:35], v[216:219], v[224:227], v[32:35]
	v_mfma_f32_16x16x32_bf16 v[40:43], v[220:223], v[224:227], v[40:43]
	s_waitcnt lgkmcnt(2)
	v_mfma_f32_16x16x32_bf16 v[52:55], v[180:183], v[228:231], v[52:55]
	v_mfma_f32_16x16x32_bf16 v[60:63], v[212:215], v[228:231], v[60:63]
	v_mfma_f32_16x16x32_bf16 v[36:39], v[216:219], v[228:231], v[36:39]
	v_mfma_f32_16x16x32_bf16 v[44:47], v[220:223], v[228:231], v[44:47]
	s_waitcnt lgkmcnt(1)
	v_mfma_f32_16x16x32_bf16 v[16:19], v[180:183], v[232:235], v[16:19]
	v_mfma_f32_16x16x32_bf16 v[24:27], v[212:215], v[232:235], v[24:27]
	v_mfma_f32_16x16x32_bf16 v[0:3], v[216:219], v[232:235], v[0:3]
	v_mfma_f32_16x16x32_bf16 v[8:11], v[220:223], v[232:235], v[8:11]
	s_waitcnt lgkmcnt(0)
	s_add_u32 s4, s4, 0x80
	s_addc_u32 s5, s5, 0
	s_add_u32 s49, s49, 0x10000
	s_sub_u32 s53, s49, 0x28000
	s_cmp_ge_u32 s49, 0x28000
	s_cselect_b32 s49, s53, s49
	s_mov_b32 s50, s51
	s_waitcnt vmcnt(0)
	s_barrier
	v_add_u32_e32 v137, s50, v134
	v_add_u32_e32 v136, s49, v132
	ds_read_b128 v[164:167], v137
	ds_read_b128 v[168:171], v137 offset:2048
	ds_read_b128 v[172:175], v137 offset:4096
	ds_read_b128 v[176:179], v137 offset:6144
	ds_read_b128 v[224:227], v136
	ds_read_b128 v[228:231], v136 offset:2048
	ds_read_b128 v[232:235], v136 offset:4096
	v_mfma_f32_16x16x32_bf16 v[20:23], v[180:183], v[236:239], v[20:23]
	v_mfma_f32_16x16x32_bf16 v[28:31], v[212:215], v[236:239], v[28:31]
	v_mfma_f32_16x16x32_bf16 v[4:7], v[216:219], v[236:239], v[4:7]
	v_mfma_f32_16x16x32_bf16 v[12:15], v[220:223], v[236:239], v[12:15]
	ds_read_b128 v[236:239], v136 offset:6144
	v_add_u32_e32 v137, s50, v135
	s_waitcnt lgkmcnt(4)
	s_waitcnt lgkmcnt(3)
	v_mfma_f32_16x16x32_bf16 v[112:115], v[164:167], v[224:227], v[112:115]
	v_mfma_f32_16x16x32_bf16 v[120:123], v[168:171], v[224:227], v[120:123]
	v_mfma_f32_16x16x32_bf16 v[96:99], v[172:175], v[224:227], v[96:99]
	v_mfma_f32_16x16x32_bf16 v[104:107], v[176:179], v[224:227], v[104:107]
	ds_read_b128 v[224:227], v136 offset:8192
	ds_read_b128 v[180:183], v137
	s_waitcnt lgkmcnt(4)
	v_mfma_f32_16x16x32_bf16 v[116:119], v[164:167], v[228:231], v[116:119]
	v_mfma_f32_16x16x32_bf16 v[124:127], v[168:171], v[228:231], v[124:127]
	v_mfma_f32_16x16x32_bf16 v[100:103], v[172:175], v[228:231], v[100:103]
	v_mfma_f32_16x16x32_bf16 v[108:111], v[176:179], v[228:231], v[108:111]
	ds_read_b128 v[228:231], v136 offset:10240
	ds_read_b128 v[212:215], v137 offset:2048
	s_waitcnt lgkmcnt(5)
	v_mfma_f32_16x16x32_bf16 v[80:83], v[164:167], v[232:235], v[80:83]
	v_mfma_f32_16x16x32_bf16 v[88:91], v[168:171], v[232:235], v[88:91]
	v_mfma_f32_16x16x32_bf16 v[64:67], v[172:175], v[232:235], v[64:67]
	v_mfma_f32_16x16x32_bf16 v[72:75], v[176:179], v[232:235], v[72:75]
	ds_read_b128 v[232:235], v136 offset:12288
	ds_read_b128 v[216:219], v137 offset:4096
	s_waitcnt lgkmcnt(6)
	v_mfma_f32_16x16x32_bf16 v[84:87], v[164:167], v[236:239], v[84:87]
	v_mfma_f32_16x16x32_bf16 v[92:95], v[168:171], v[236:239], v[92:95]
	v_mfma_f32_16x16x32_bf16 v[68:71], v[172:175], v[236:239], v[68:71]
	v_mfma_f32_16x16x32_bf16 v[76:79], v[176:179], v[236:239], v[76:79]
	ds_read_b128 v[236:239], v136 offset:14336
	ds_read_b128 v[220:223], v137 offset:6144
	v_add_u32_e32 v136, s49, v133
	s_waitcnt lgkmcnt(7)
	v_mfma_f32_16x16x32_bf16 v[48:51], v[164:167], v[224:227], v[48:51]
	v_mfma_f32_16x16x32_bf16 v[56:59], v[168:171], v[224:227], v[56:59]
	v_mfma_f32_16x16x32_bf16 v[32:35], v[172:175], v[224:227], v[32:35]
	v_mfma_f32_16x16x32_bf16 v[40:43], v[176:179], v[224:227], v[40:43]
	ds_read_b128 v[224:227], v136
	s_waitcnt lgkmcnt(6)
	v_mfma_f32_16x16x32_bf16 v[52:55], v[164:167], v[228:231], v[52:55]
	v_mfma_f32_16x16x32_bf16 v[60:63], v[168:171], v[228:231], v[60:63]
	v_mfma_f32_16x16x32_bf16 v[36:39], v[172:175], v[228:231], v[36:39]
	v_mfma_f32_16x16x32_bf16 v[44:47], v[176:179], v[228:231], v[44:47]
	ds_read_b128 v[228:231], v136 offset:2048
	s_waitcnt lgkmcnt(5)
	v_mfma_f32_16x16x32_bf16 v[16:19], v[164:167], v[232:235], v[16:19]
	v_mfma_f32_16x16x32_bf16 v[24:27], v[168:171], v[232:235], v[24:27]
	v_mfma_f32_16x16x32_bf16 v[0:3], v[172:175], v[232:235], v[0:3]
	v_mfma_f32_16x16x32_bf16 v[8:11], v[176:179], v[232:235], v[8:11]
	ds_read_b128 v[232:235], v136 offset:4096
	s_waitcnt lgkmcnt(4)
	v_mfma_f32_16x16x32_bf16 v[20:23], v[164:167], v[236:239], v[20:23]
	v_mfma_f32_16x16x32_bf16 v[28:31], v[168:171], v[236:239], v[28:31]
	v_mfma_f32_16x16x32_bf16 v[4:7], v[172:175], v[236:239], v[4:7]
	v_mfma_f32_16x16x32_bf16 v[12:15], v[176:179], v[236:239], v[12:15]
	ds_read_b128 v[236:239], v136 offset:6144
	s_waitcnt lgkmcnt(4)
	s_waitcnt lgkmcnt(3)
	v_mfma_f32_16x16x32_bf16 v[112:115], v[180:183], v[224:227], v[112:115]
	v_mfma_f32_16x16x32_bf16 v[120:123], v[212:215], v[224:227], v[120:123]
	v_mfma_f32_16x16x32_bf16 v[96:99], v[216:219], v[224:227], v[96:99]
	v_mfma_f32_16x16x32_bf16 v[104:107], v[220:223], v[224:227], v[104:107]
	ds_read_b128 v[224:227], v136 offset:8192
	s_waitcnt lgkmcnt(3)
	v_mfma_f32_16x16x32_bf16 v[116:119], v[180:183], v[228:231], v[116:119]
	v_mfma_f32_16x16x32_bf16 v[124:127], v[212:215], v[228:231], v[124:127]
	v_mfma_f32_16x16x32_bf16 v[100:103], v[216:219], v[228:231], v[100:103]
	v_mfma_f32_16x16x32_bf16 v[108:111], v[220:223], v[228:231], v[108:111]
	ds_read_b128 v[228:231], v136 offset:10240
	s_waitcnt lgkmcnt(3)
	v_mfma_f32_16x16x32_bf16 v[80:83], v[180:183], v[232:235], v[80:83]
	v_mfma_f32_16x16x32_bf16 v[88:91], v[212:215], v[232:235], v[88:91]
	v_mfma_f32_16x16x32_bf16 v[64:67], v[216:219], v[232:235], v[64:67]
	v_mfma_f32_16x16x32_bf16 v[72:75], v[220:223], v[232:235], v[72:75]
	ds_read_b128 v[232:235], v136 offset:12288
	s_waitcnt lgkmcnt(3)
	v_mfma_f32_16x16x32_bf16 v[84:87], v[180:183], v[236:239], v[84:87]
	v_mfma_f32_16x16x32_bf16 v[92:95], v[212:215], v[236:239], v[92:95]
	v_mfma_f32_16x16x32_bf16 v[68:71], v[216:219], v[236:239], v[68:71]
	v_mfma_f32_16x16x32_bf16 v[76:79], v[220:223], v[236:239], v[76:79]
	ds_read_b128 v[236:239], v136 offset:14336
	s_waitcnt lgkmcnt(3)
	v_mfma_f32_16x16x32_bf16 v[48:51], v[180:183], v[224:227], v[48:51]
	v_mfma_f32_16x16x32_bf16 v[56:59], v[212:215], v[224:227], v[56:59]
	v_mfma_f32_16x16x32_bf16 v[32:35], v[216:219], v[224:227], v[32:35]
	v_mfma_f32_16x16x32_bf16 v[40:43], v[220:223], v[224:227], v[40:43]
	s_waitcnt lgkmcnt(2)
	v_mfma_f32_16x16x32_bf16 v[52:55], v[180:183], v[228:231], v[52:55]
	v_mfma_f32_16x16x32_bf16 v[60:63], v[212:215], v[228:231], v[60:63]
	v_mfma_f32_16x16x32_bf16 v[36:39], v[216:219], v[228:231], v[36:39]
	v_mfma_f32_16x16x32_bf16 v[44:47], v[220:223], v[228:231], v[44:47]
	s_waitcnt lgkmcnt(1)
	v_mfma_f32_16x16x32_bf16 v[16:19], v[180:183], v[232:235], v[16:19]
	v_mfma_f32_16x16x32_bf16 v[24:27], v[212:215], v[232:235], v[24:27]
	v_mfma_f32_16x16x32_bf16 v[0:3], v[216:219], v[232:235], v[0:3]
	v_mfma_f32_16x16x32_bf16 v[8:11], v[220:223], v[232:235], v[8:11]
	s_waitcnt lgkmcnt(0)
	s_waitcnt vmcnt(0)
	s_barrier
	v_mfma_f32_16x16x32_bf16 v[20:23], v[180:183], v[236:239], v[20:23]
	v_mfma_f32_16x16x32_bf16 v[28:31], v[212:215], v[236:239], v[28:31]
	v_mfma_f32_16x16x32_bf16 v[4:7], v[216:219], v[236:239], v[4:7]
	v_mfma_f32_16x16x32_bf16 v[12:15], v[220:223], v[236:239], v[12:15]
	s_nop 15
	v_permlane16_swap_b32_e32 v112, v116
	v_permlane16_swap_b32_e32 v113, v117
	v_permlane16_swap_b32_e32 v114, v118
	v_permlane16_swap_b32_e32 v115, v119
	v_permlane16_swap_b32_e32 v120, v124
	v_permlane16_swap_b32_e32 v121, v125
	v_permlane16_swap_b32_e32 v122, v126
	v_permlane16_swap_b32_e32 v123, v127
	v_permlane16_swap_b32_e32 v96, v100
	v_permlane16_swap_b32_e32 v97, v101
	v_permlane16_swap_b32_e32 v98, v102
	v_permlane16_swap_b32_e32 v99, v103
	v_permlane16_swap_b32_e32 v104, v108
	v_permlane16_swap_b32_e32 v105, v109
	v_permlane16_swap_b32_e32 v106, v110
	v_permlane16_swap_b32_e32 v107, v111
	v_permlane16_swap_b32_e32 v80, v84
	v_permlane16_swap_b32_e32 v81, v85
	v_permlane16_swap_b32_e32 v82, v86
	v_permlane16_swap_b32_e32 v83, v87
	v_permlane16_swap_b32_e32 v88, v92
	v_permlane16_swap_b32_e32 v89, v93
	v_permlane16_swap_b32_e32 v90, v94
	v_permlane16_swap_b32_e32 v91, v95
	v_permlane16_swap_b32_e32 v64, v68
	v_permlane16_swap_b32_e32 v65, v69
	v_permlane16_swap_b32_e32 v66, v70
	v_permlane16_swap_b32_e32 v67, v71
	v_permlane16_swap_b32_e32 v72, v76
	v_permlane16_swap_b32_e32 v73, v77
	v_permlane16_swap_b32_e32 v74, v78
	v_permlane16_swap_b32_e32 v75, v79
	v_permlane16_swap_b32_e32 v48, v52
	v_permlane16_swap_b32_e32 v49, v53
	v_permlane16_swap_b32_e32 v50, v54
	v_permlane16_swap_b32_e32 v51, v55
	v_permlane16_swap_b32_e32 v56, v60
	v_permlane16_swap_b32_e32 v57, v61
	v_permlane16_swap_b32_e32 v58, v62
	v_permlane16_swap_b32_e32 v59, v63
	v_permlane16_swap_b32_e32 v32, v36
	v_permlane16_swap_b32_e32 v33, v37
	v_permlane16_swap_b32_e32 v34, v38
	v_permlane16_swap_b32_e32 v35, v39
	v_permlane16_swap_b32_e32 v40, v44
	v_permlane16_swap_b32_e32 v41, v45
	v_permlane16_swap_b32_e32 v42, v46
	v_permlane16_swap_b32_e32 v43, v47
	v_permlane16_swap_b32_e32 v16, v20
	v_permlane16_swap_b32_e32 v17, v21
	v_permlane16_swap_b32_e32 v18, v22
	v_permlane16_swap_b32_e32 v19, v23
	v_permlane16_swap_b32_e32 v24, v28
	v_permlane16_swap_b32_e32 v25, v29
	v_permlane16_swap_b32_e32 v26, v30
	v_permlane16_swap_b32_e32 v27, v31
	v_permlane16_swap_b32_e32 v0, v4
	v_permlane16_swap_b32_e32 v1, v5
	v_permlane16_swap_b32_e32 v2, v6
	v_permlane16_swap_b32_e32 v3, v7
	v_permlane16_swap_b32_e32 v8, v12
	v_permlane16_swap_b32_e32 v9, v13
	v_permlane16_swap_b32_e32 v10, v14
	v_permlane16_swap_b32_e32 v11, v15
	v_permlane32_swap_b32_e32 v112, v116
	v_permlane32_swap_b32_e32 v113, v117
	v_permlane32_swap_b32_e32 v114, v118
	v_permlane32_swap_b32_e32 v115, v119
	v_permlane32_swap_b32_e32 v120, v124
	v_permlane32_swap_b32_e32 v121, v125
	v_permlane32_swap_b32_e32 v122, v126
	v_permlane32_swap_b32_e32 v123, v127
	v_permlane32_swap_b32_e32 v96, v100
	v_permlane32_swap_b32_e32 v97, v101
	v_permlane32_swap_b32_e32 v98, v102
	v_permlane32_swap_b32_e32 v99, v103
	v_permlane32_swap_b32_e32 v104, v108
	v_permlane32_swap_b32_e32 v105, v109
	v_permlane32_swap_b32_e32 v106, v110
	v_permlane32_swap_b32_e32 v107, v111
	v_permlane32_swap_b32_e32 v80, v84
	v_permlane32_swap_b32_e32 v81, v85
	v_permlane32_swap_b32_e32 v82, v86
	v_permlane32_swap_b32_e32 v83, v87
	v_permlane32_swap_b32_e32 v88, v92
	v_permlane32_swap_b32_e32 v89, v93
	v_permlane32_swap_b32_e32 v90, v94
	v_permlane32_swap_b32_e32 v91, v95
	v_permlane32_swap_b32_e32 v64, v68
	v_permlane32_swap_b32_e32 v65, v69
	v_permlane32_swap_b32_e32 v66, v70
	v_permlane32_swap_b32_e32 v67, v71
	v_permlane32_swap_b32_e32 v72, v76
	v_permlane32_swap_b32_e32 v73, v77
	v_permlane32_swap_b32_e32 v74, v78
	v_permlane32_swap_b32_e32 v75, v79
	v_permlane32_swap_b32_e32 v48, v52
	v_permlane32_swap_b32_e32 v49, v53
	v_permlane32_swap_b32_e32 v50, v54
	v_permlane32_swap_b32_e32 v51, v55
	v_permlane32_swap_b32_e32 v56, v60
	v_permlane32_swap_b32_e32 v57, v61
	v_permlane32_swap_b32_e32 v58, v62
	v_permlane32_swap_b32_e32 v59, v63
	v_permlane32_swap_b32_e32 v32, v36
	v_permlane32_swap_b32_e32 v33, v37
	v_permlane32_swap_b32_e32 v34, v38
	v_permlane32_swap_b32_e32 v35, v39
	v_permlane32_swap_b32_e32 v40, v44
	v_permlane32_swap_b32_e32 v41, v45
	v_permlane32_swap_b32_e32 v42, v46
	v_permlane32_swap_b32_e32 v43, v47
	v_permlane32_swap_b32_e32 v16, v20
	v_permlane32_swap_b32_e32 v17, v21
	v_permlane32_swap_b32_e32 v18, v22
	v_permlane32_swap_b32_e32 v19, v23
	v_permlane32_swap_b32_e32 v24, v28
	v_permlane32_swap_b32_e32 v25, v29
	v_permlane32_swap_b32_e32 v26, v30
	v_permlane32_swap_b32_e32 v27, v31
	v_permlane32_swap_b32_e32 v0, v4
	v_permlane32_swap_b32_e32 v1, v5
	v_permlane32_swap_b32_e32 v2, v6
	v_permlane32_swap_b32_e32 v3, v7
	v_permlane32_swap_b32_e32 v8, v12
	v_permlane32_swap_b32_e32 v9, v13
	v_permlane32_swap_b32_e32 v10, v14
	v_permlane32_swap_b32_e32 v11, v15
	s_nop 1

.Lg162_loop:
	s_add_u32 s51, s50, 0x10000
	s_sub_u32 s53, s51, 0x28000
	s_cmp_ge_u32 s51, 0x28000
	s_cselect_b32 s51, s53, s51
	s_add_u32 s52, s49, 0x20000
	s_sub_u32 s53, s52, 0x28000
	s_cmp_ge_u32 s52, 0x28000
	s_cselect_b32 s52, s53, s52
	v_add_u32_e32 v167, s50, v145
	s_waitcnt lgkmcnt(4)
	s_waitcnt lgkmcnt(3)
	v_mfma_f32_16x16x32_bf16 v[112:115], v[188:191], v[220:223], v[112:115]
	v_mfma_f32_16x16x32_bf16 v[120:123], v[192:195], v[220:223], v[120:123]
	v_mfma_f32_16x16x32_bf16 v[96:99], v[196:199], v[220:223], v[96:99]
	v_mfma_f32_16x16x32_bf16 v[104:107], v[200:203], v[220:223], v[104:107]
	s_add_u32 m0, s51, s48
	s_nop 0
	global_load_lds_dwordx4 v169, s[64:65]
	s_add_u32 s64, s64, 0x80
	s_addc_u32 s65, s65, 0
	s_add_u32 s53, s51, s48
	s_add_u32 m0, s53, 0x2000
	s_nop 0
	global_load_lds_dwordx4 v169, s[66:67]
	s_add_u32 s66, s66, 0x80
	s_addc_u32 s67, s67, 0
	ds_read_b128 v[220:223], v166 offset:8192
	ds_read_b128 v[204:207], v167
	s_waitcnt lgkmcnt(4)
	v_mfma_f32_16x16x32_bf16 v[116:119], v[188:191], v[224:227], v[116:119]
	v_mfma_f32_16x16x32_bf16 v[124:127], v[192:195], v[224:227], v[124:127]
	v_mfma_f32_16x16x32_bf16 v[100:103], v[196:199], v[224:227], v[100:103]
	v_mfma_f32_16x16x32_bf16 v[108:111], v[200:203], v[224:227], v[108:111]
	s_add_u32 s53, s51, s48
	s_add_u32 m0, s53, 0x4000
	s_nop 0
	global_load_lds_dwordx4 v169, s[68:69]
	s_add_u32 s68, s68, 0x80
	s_addc_u32 s69, s69, 0
	s_add_u32 s53, s51, s48
	s_add_u32 m0, s53, 0x6000
	s_nop 0
	global_load_lds_dwordx4 v169, s[70:71]
	s_add_u32 s70, s70, 0x80
	s_addc_u32 s71, s71, 0
	ds_read_b128 v[224:227], v166 offset:10240
	ds_read_b128 v[208:211], v167 offset:2048
	s_waitcnt lgkmcnt(5)
	v_mfma_f32_16x16x32_bf16 v[80:83], v[188:191], v[228:231], v[80:83]
	v_mfma_f32_16x16x32_bf16 v[88:91], v[192:195], v[228:231], v[88:91]
	v_mfma_f32_16x16x32_bf16 v[64:67], v[196:199], v[228:231], v[64:67]
	v_mfma_f32_16x16x32_bf16 v[72:75], v[200:203], v[228:231], v[72:75]
	ds_read_b128 v[228:231], v166 offset:12288
	ds_read_b128 v[212:215], v167 offset:4096
	s_waitcnt lgkmcnt(6)
	v_mfma_f32_16x16x32_bf16 v[84:87], v[188:191], v[232:235], v[84:87]
	v_mfma_f32_16x16x32_bf16 v[92:95], v[192:195], v[232:235], v[92:95]
	v_mfma_f32_16x16x32_bf16 v[68:71], v[196:199], v[232:235], v[68:71]
	v_mfma_f32_16x16x32_bf16 v[76:79], v[200:203], v[232:235], v[76:79]
	ds_read_b128 v[232:235], v166 offset:14336
	ds_read_b128 v[216:219], v167 offset:6144
	v_add_u32_e32 v166, s49, v143
	s_waitcnt lgkmcnt(7)
	v_mfma_f32_16x16x32_bf16 v[48:51], v[188:191], v[220:223], v[48:51]
	v_mfma_f32_16x16x32_bf16 v[56:59], v[192:195], v[220:223], v[56:59]
	v_mfma_f32_16x16x32_bf16 v[32:35], v[196:199], v[220:223], v[32:35]
	v_mfma_f32_16x16x32_bf16 v[40:43], v[200:203], v[220:223], v[40:43]
	ds_read_b128 v[220:223], v166
	s_waitcnt lgkmcnt(6)
	v_mfma_f32_16x16x32_bf16 v[52:55], v[188:191], v[224:227], v[52:55]
	v_mfma_f32_16x16x32_bf16 v[60:63], v[192:195], v[224:227], v[60:63]
	v_mfma_f32_16x16x32_bf16 v[36:39], v[196:199], v[224:227], v[36:39]
	v_mfma_f32_16x16x32_bf16 v[44:47], v[200:203], v[224:227], v[44:47]
	ds_read_b128 v[224:227], v166 offset:2048
	s_waitcnt lgkmcnt(5)
	v_mfma_f32_16x16x32_bf16 v[16:19], v[188:191], v[228:231], v[16:19]
	v_mfma_f32_16x16x32_bf16 v[24:27], v[192:195], v[228:231], v[24:27]
	v_mfma_f32_16x16x32_bf16 v[0:3], v[196:199], v[228:231], v[0:3]
	v_mfma_f32_16x16x32_bf16 v[8:11], v[200:203], v[228:231], v[8:11]
	ds_read_b128 v[228:231], v166 offset:4096
	s_waitcnt lgkmcnt(4)
	v_mfma_f32_16x16x32_bf16 v[20:23], v[188:191], v[232:235], v[20:23]
	v_mfma_f32_16x16x32_bf16 v[28:31], v[192:195], v[232:235], v[28:31]
	v_mfma_f32_16x16x32_bf16 v[4:7], v[196:199], v[232:235], v[4:7]
	v_mfma_f32_16x16x32_bf16 v[12:15], v[200:203], v[232:235], v[12:15]
	ds_read_b128 v[232:235], v166 offset:6144
	s_waitcnt lgkmcnt(4)
	s_waitcnt lgkmcnt(3)
	v_mfma_f32_16x16x32_bf16 v[112:115], v[204:207], v[220:223], v[112:115]
	v_mfma_f32_16x16x32_bf16 v[120:123], v[208:211], v[220:223], v[120:123]
	v_mfma_f32_16x16x32_bf16 v[96:99], v[212:215], v[220:223], v[96:99]
	v_mfma_f32_16x16x32_bf16 v[104:107], v[216:219], v[220:223], v[104:107]
	ds_read_b128 v[220:223], v166 offset:8192
	s_waitcnt lgkmcnt(3)
	v_mfma_f32_16x16x32_bf16 v[116:119], v[204:207], v[224:227], v[116:119]
	v_mfma_f32_16x16x32_bf16 v[124:127], v[208:211], v[224:227], v[124:127]
	v_mfma_f32_16x16x32_bf16 v[100:103], v[212:215], v[224:227], v[100:103]
	v_mfma_f32_16x16x32_bf16 v[108:111], v[216:219], v[224:227], v[108:111]
	ds_read_b128 v[224:227], v166 offset:10240
	s_waitcnt lgkmcnt(3)
	v_mfma_f32_16x16x32_bf16 v[80:83], v[204:207], v[228:231], v[80:83]
	v_mfma_f32_16x16x32_bf16 v[88:91], v[208:211], v[228:231], v[88:91]
	v_mfma_f32_16x16x32_bf16 v[64:67], v[212:215], v[228:231], v[64:67]
	v_mfma_f32_16x16x32_bf16 v[72:75], v[216:219], v[228:231], v[72:75]
	ds_read_b128 v[228:231], v166 offset:12288
	s_waitcnt lgkmcnt(3)
	v_mfma_f32_16x16x32_bf16 v[84:87], v[204:207], v[232:235], v[84:87]
	v_mfma_f32_16x16x32_bf16 v[92:95], v[208:211], v[232:235], v[92:95]
	v_mfma_f32_16x16x32_bf16 v[68:71], v[212:215], v[232:235], v[68:71]
	v_mfma_f32_16x16x32_bf16 v[76:79], v[216:219], v[232:235], v[76:79]
	ds_read_b128 v[232:235], v166 offset:14336
	s_waitcnt lgkmcnt(3)
	v_mfma_f32_16x16x32_bf16 v[48:51], v[204:207], v[220:223], v[48:51]
	v_mfma_f32_16x16x32_bf16 v[56:59], v[208:211], v[220:223], v[56:59]
	v_mfma_f32_16x16x32_bf16 v[32:35], v[212:215], v[220:223], v[32:35]
	v_mfma_f32_16x16x32_bf16 v[40:43], v[216:219], v[220:223], v[40:43]
	s_add_u32 m0, s52, s48
	s_nop 0
	global_load_lds_dwordx4 v168, s[56:57]
	s_add_u32 s56, s56, 0x80
	s_addc_u32 s57, s57, 0
	s_add_u32 s53, s52, s48
	s_add_u32 m0, s53, 0x2000
	s_nop 0
	global_load_lds_dwordx4 v168, s[58:59]
	s_add_u32 s58, s58, 0x80
	s_addc_u32 s59, s59, 0
	s_waitcnt lgkmcnt(2)
	v_mfma_f32_16x16x32_bf16 v[52:55], v[204:207], v[224:227], v[52:55]
	v_mfma_f32_16x16x32_bf16 v[60:63], v[208:211], v[224:227], v[60:63]
	v_mfma_f32_16x16x32_bf16 v[36:39], v[212:215], v[224:227], v[36:39]
	v_mfma_f32_16x16x32_bf16 v[44:47], v[216:219], v[224:227], v[44:47]
	s_add_u32 s53, s52, s48
	s_add_u32 m0, s53, 0x4000
	s_nop 0
	global_load_lds_dwordx4 v168, s[60:61]
	s_add_u32 s60, s60, 0x80
	s_addc_u32 s61, s61, 0
	s_add_u32 s53, s52, s48
	s_add_u32 m0, s53, 0x6000
	s_nop 0
	global_load_lds_dwordx4 v168, s[62:63]
	s_add_u32 s62, s62, 0x80
	s_addc_u32 s63, s63, 0
	s_waitcnt lgkmcnt(1)
	v_mfma_f32_16x16x32_bf16 v[16:19], v[204:207], v[228:231], v[16:19]
	v_mfma_f32_16x16x32_bf16 v[24:27], v[208:211], v[228:231], v[24:27]
	v_mfma_f32_16x16x32_bf16 v[0:3], v[212:215], v[228:231], v[0:3]
	v_mfma_f32_16x16x32_bf16 v[8:11], v[216:219], v[228:231], v[8:11]
	s_waitcnt lgkmcnt(0)
	s_add_u32 s28, s28, 0x80
	s_addc_u32 s29, s29, 0
	s_add_u32 s49, s49, 0x10000
	s_sub_u32 s53, s49, 0x28000
	s_cmp_ge_u32 s49, 0x28000
	s_cselect_b32 s49, s53, s49
	s_mov_b32 s50, s51
	s_waitcnt vmcnt(4)
	s_barrier
	v_add_u32_e32 v167, s50, v144
	v_add_u32_e32 v166, s49, v142
	ds_read_b128 v[188:191], v167
	ds_read_b128 v[192:195], v167 offset:2048
	ds_read_b128 v[196:199], v167 offset:4096
	ds_read_b128 v[200:203], v167 offset:6144
	ds_read_b128 v[220:223], v166
	ds_read_b128 v[224:227], v166 offset:2048
	ds_read_b128 v[228:231], v166 offset:4096
	v_mfma_f32_16x16x32_bf16 v[20:23], v[204:207], v[232:235], v[20:23]
	v_mfma_f32_16x16x32_bf16 v[28:31], v[208:211], v[232:235], v[28:31]
	v_mfma_f32_16x16x32_bf16 v[4:7], v[212:215], v[232:235], v[4:7]
	v_mfma_f32_16x16x32_bf16 v[12:15], v[216:219], v[232:235], v[12:15]
	ds_read_b128 v[232:235], v166 offset:6144
	s_cmpk_lg_i32 s28, 0xf00
	s_cbranch_scc1 .Lg162_loop
	s_add_u32 s51, s50, 0x10000
	s_sub_u32 s53, s51, 0x28000
	s_cmp_ge_u32 s51, 0x28000
	s_cselect_b32 s51, s53, s51
	v_add_u32_e32 v167, s50, v145
	s_waitcnt lgkmcnt(4)
	s_waitcnt lgkmcnt(3)
	v_mfma_f32_16x16x32_bf16 v[112:115], v[188:191], v[220:223], v[112:115]
	v_mfma_f32_16x16x32_bf16 v[120:123], v[192:195], v[220:223], v[120:123]
	v_mfma_f32_16x16x32_bf16 v[96:99], v[196:199], v[220:223], v[96:99]
	v_mfma_f32_16x16x32_bf16 v[104:107], v[200:203], v[220:223], v[104:107]
	s_add_u32 m0, s51, s48
	s_nop 0
	global_load_lds_dwordx4 v169, s[64:65]
	s_add_u32 s64, s64, 0x80
	s_addc_u32 s65, s65, 0
	s_add_u32 s53, s51, s48
	s_add_u32 m0, s53, 0x2000
	s_nop 0
	global_load_lds_dwordx4 v169, s[66:67]
	s_add_u32 s66, s66, 0x80
	s_addc_u32 s67, s67, 0
	ds_read_b128 v[220:223], v166 offset:8192
	ds_read_b128 v[204:207], v167
	s_waitcnt lgkmcnt(4)
	v_mfma_f32_16x16x32_bf16 v[116:119], v[188:191], v[224:227], v[116:119]
	v_mfma_f32_16x16x32_bf16 v[124:127], v[192:195], v[224:227], v[124:127]
	v_mfma_f32_16x16x32_bf16 v[100:103], v[196:199], v[224:227], v[100:103]
	v_mfma_f32_16x16x32_bf16 v[108:111], v[200:203], v[224:227], v[108:111]
	s_add_u32 s53, s51, s48
	s_add_u32 m0, s53, 0x4000
	s_nop 0
	global_load_lds_dwordx4 v169, s[68:69]
	s_add_u32 s68, s68, 0x80
	s_addc_u32 s69, s69, 0
	s_add_u32 s53, s51, s48
	s_add_u32 m0, s53, 0x6000
	s_nop 0
	global_load_lds_dwordx4 v169, s[70:71]
	s_add_u32 s70, s70, 0x80
	s_addc_u32 s71, s71, 0
	ds_read_b128 v[224:227], v166 offset:10240
	ds_read_b128 v[208:211], v167 offset:2048
	s_waitcnt lgkmcnt(5)
	v_mfma_f32_16x16x32_bf16 v[80:83], v[188:191], v[228:231], v[80:83]
	v_mfma_f32_16x16x32_bf16 v[88:91], v[192:195], v[228:231], v[88:91]
	v_mfma_f32_16x16x32_bf16 v[64:67], v[196:199], v[228:231], v[64:67]
	v_mfma_f32_16x16x32_bf16 v[72:75], v[200:203], v[228:231], v[72:75]
	ds_read_b128 v[228:231], v166 offset:12288
	ds_read_b128 v[212:215], v167 offset:4096
	s_waitcnt lgkmcnt(6)
	v_mfma_f32_16x16x32_bf16 v[84:87], v[188:191], v[232:235], v[84:87]
	v_mfma_f32_16x16x32_bf16 v[92:95], v[192:195], v[232:235], v[92:95]
	v_mfma_f32_16x16x32_bf16 v[68:71], v[196:199], v[232:235], v[68:71]
	v_mfma_f32_16x16x32_bf16 v[76:79], v[200:203], v[232:235], v[76:79]
	ds_read_b128 v[232:235], v166 offset:14336
	ds_read_b128 v[216:219], v167 offset:6144
	v_add_u32_e32 v166, s49, v143
	s_waitcnt lgkmcnt(7)
	v_mfma_f32_16x16x32_bf16 v[48:51], v[188:191], v[220:223], v[48:51]
	v_mfma_f32_16x16x32_bf16 v[56:59], v[192:195], v[220:223], v[56:59]
	v_mfma_f32_16x16x32_bf16 v[32:35], v[196:199], v[220:223], v[32:35]
	v_mfma_f32_16x16x32_bf16 v[40:43], v[200:203], v[220:223], v[40:43]
	ds_read_b128 v[220:223], v166
	s_waitcnt lgkmcnt(6)
	v_mfma_f32_16x16x32_bf16 v[52:55], v[188:191], v[224:227], v[52:55]
	v_mfma_f32_16x16x32_bf16 v[60:63], v[192:195], v[224:227], v[60:63]
	v_mfma_f32_16x16x32_bf16 v[36:39], v[196:199], v[224:227], v[36:39]
	v_mfma_f32_16x16x32_bf16 v[44:47], v[200:203], v[224:227], v[44:47]
	ds_read_b128 v[224:227], v166 offset:2048
	s_waitcnt lgkmcnt(5)
	v_mfma_f32_16x16x32_bf16 v[16:19], v[188:191], v[228:231], v[16:19]
	v_mfma_f32_16x16x32_bf16 v[24:27], v[192:195], v[228:231], v[24:27]
	v_mfma_f32_16x16x32_bf16 v[0:3], v[196:199], v[228:231], v[0:3]
	v_mfma_f32_16x16x32_bf16 v[8:11], v[200:203], v[228:231], v[8:11]
	ds_read_b128 v[228:231], v166 offset:4096
	s_waitcnt lgkmcnt(4)
	v_mfma_f32_16x16x32_bf16 v[20:23], v[188:191], v[232:235], v[20:23]
	v_mfma_f32_16x16x32_bf16 v[28:31], v[192:195], v[232:235], v[28:31]
	v_mfma_f32_16x16x32_bf16 v[4:7], v[196:199], v[232:235], v[4:7]
	v_mfma_f32_16x16x32_bf16 v[12:15], v[200:203], v[232:235], v[12:15]
	ds_read_b128 v[232:235], v166 offset:6144
	s_waitcnt lgkmcnt(4)
	s_waitcnt lgkmcnt(3)
	v_mfma_f32_16x16x32_bf16 v[112:115], v[204:207], v[220:223], v[112:115]
	v_mfma_f32_16x16x32_bf16 v[120:123], v[208:211], v[220:223], v[120:123]
	v_mfma_f32_16x16x32_bf16 v[96:99], v[212:215], v[220:223], v[96:99]
	v_mfma_f32_16x16x32_bf16 v[104:107], v[216:219], v[220:223], v[104:107]
	ds_read_b128 v[220:223], v166 offset:8192
	s_waitcnt lgkmcnt(3)
	v_mfma_f32_16x16x32_bf16 v[116:119], v[204:207], v[224:227], v[116:119]
	v_mfma_f32_16x16x32_bf16 v[124:127], v[208:211], v[224:227], v[124:127]
	v_mfma_f32_16x16x32_bf16 v[100:103], v[212:215], v[224:227], v[100:103]
	v_mfma_f32_16x16x32_bf16 v[108:111], v[216:219], v[224:227], v[108:111]
	ds_read_b128 v[224:227], v166 offset:10240
	s_waitcnt lgkmcnt(3)
	v_mfma_f32_16x16x32_bf16 v[80:83], v[204:207], v[228:231], v[80:83]
	v_mfma_f32_16x16x32_bf16 v[88:91], v[208:211], v[228:231], v[88:91]
	v_mfma_f32_16x16x32_bf16 v[64:67], v[212:215], v[228:231], v[64:67]
	v_mfma_f32_16x16x32_bf16 v[72:75], v[216:219], v[228:231], v[72:75]
	ds_read_b128 v[228:231], v166 offset:12288
	s_waitcnt lgkmcnt(3)
	v_mfma_f32_16x16x32_bf16 v[84:87], v[204:207], v[232:235], v[84:87]
	v_mfma_f32_16x16x32_bf16 v[92:95], v[208:211], v[232:235], v[92:95]
	v_mfma_f32_16x16x32_bf16 v[68:71], v[212:215], v[232:235], v[68:71]
	v_mfma_f32_16x16x32_bf16 v[76:79], v[216:219], v[232:235], v[76:79]
	ds_read_b128 v[232:235], v166 offset:14336
	s_waitcnt lgkmcnt(3)
	v_mfma_f32_16x16x32_bf16 v[48:51], v[204:207], v[220:223], v[48:51]
	v_mfma_f32_16x16x32_bf16 v[56:59], v[208:211], v[220:223], v[56:59]
	v_mfma_f32_16x16x32_bf16 v[32:35], v[212:215], v[220:223], v[32:35]
	v_mfma_f32_16x16x32_bf16 v[40:43], v[216:219], v[220:223], v[40:43]
	s_waitcnt lgkmcnt(2)
	v_mfma_f32_16x16x32_bf16 v[52:55], v[204:207], v[224:227], v[52:55]
	v_mfma_f32_16x16x32_bf16 v[60:63], v[208:211], v[224:227], v[60:63]
	v_mfma_f32_16x16x32_bf16 v[36:39], v[212:215], v[224:227], v[36:39]
	v_mfma_f32_16x16x32_bf16 v[44:47], v[216:219], v[224:227], v[44:47]
	s_waitcnt lgkmcnt(1)
	v_mfma_f32_16x16x32_bf16 v[16:19], v[204:207], v[228:231], v[16:19]
	v_mfma_f32_16x16x32_bf16 v[24:27], v[208:211], v[228:231], v[24:27]
	v_mfma_f32_16x16x32_bf16 v[0:3], v[212:215], v[228:231], v[0:3]
	v_mfma_f32_16x16x32_bf16 v[8:11], v[216:219], v[228:231], v[8:11]
	s_waitcnt lgkmcnt(0)
	s_add_u32 s28, s28, 0x80
	s_addc_u32 s29, s29, 0
	s_add_u32 s49, s49, 0x10000
	s_sub_u32 s53, s49, 0x28000
	s_cmp_ge_u32 s49, 0x28000
	s_cselect_b32 s49, s53, s49
	s_mov_b32 s50, s51
	s_waitcnt vmcnt(0)
	s_barrier
	v_add_u32_e32 v167, s50, v144
	v_add_u32_e32 v166, s49, v142
	ds_read_b128 v[188:191], v167
	ds_read_b128 v[192:195], v167 offset:2048
	ds_read_b128 v[196:199], v167 offset:4096
	ds_read_b128 v[200:203], v167 offset:6144
	ds_read_b128 v[220:223], v166
	ds_read_b128 v[224:227], v166 offset:2048
	ds_read_b128 v[228:231], v166 offset:4096
	v_mfma_f32_16x16x32_bf16 v[20:23], v[204:207], v[232:235], v[20:23]
	v_mfma_f32_16x16x32_bf16 v[28:31], v[208:211], v[232:235], v[28:31]
	v_mfma_f32_16x16x32_bf16 v[4:7], v[212:215], v[232:235], v[4:7]
	v_mfma_f32_16x16x32_bf16 v[12:15], v[216:219], v[232:235], v[12:15]
	ds_read_b128 v[232:235], v166 offset:6144
	v_add_u32_e32 v167, s50, v145
	s_waitcnt lgkmcnt(4)
	s_waitcnt lgkmcnt(3)
	v_mfma_f32_16x16x32_bf16 v[112:115], v[188:191], v[220:223], v[112:115]
	v_mfma_f32_16x16x32_bf16 v[120:123], v[192:195], v[220:223], v[120:123]
	v_mfma_f32_16x16x32_bf16 v[96:99], v[196:199], v[220:223], v[96:99]
	v_mfma_f32_16x16x32_bf16 v[104:107], v[200:203], v[220:223], v[104:107]
	ds_read_b128 v[220:223], v166 offset:8192
	ds_read_b128 v[204:207], v167
	s_waitcnt lgkmcnt(4)
	v_mfma_f32_16x16x32_bf16 v[116:119], v[188:191], v[224:227], v[116:119]
	v_mfma_f32_16x16x32_bf16 v[124:127], v[192:195], v[224:227], v[124:127]
	v_mfma_f32_16x16x32_bf16 v[100:103], v[196:199], v[224:227], v[100:103]
	v_mfma_f32_16x16x32_bf16 v[108:111], v[200:203], v[224:227], v[108:111]
	ds_read_b128 v[224:227], v166 offset:10240
	ds_read_b128 v[208:211], v167 offset:2048
	s_waitcnt lgkmcnt(5)
	v_mfma_f32_16x16x32_bf16 v[80:83], v[188:191], v[228:231], v[80:83]
	v_mfma_f32_16x16x32_bf16 v[88:91], v[192:195], v[228:231], v[88:91]
	v_mfma_f32_16x16x32_bf16 v[64:67], v[196:199], v[228:231], v[64:67]
	v_mfma_f32_16x16x32_bf16 v[72:75], v[200:203], v[228:231], v[72:75]
	ds_read_b128 v[228:231], v166 offset:12288
	ds_read_b128 v[212:215], v167 offset:4096
	s_waitcnt lgkmcnt(6)
	v_mfma_f32_16x16x32_bf16 v[84:87], v[188:191], v[232:235], v[84:87]
	v_mfma_f32_16x16x32_bf16 v[92:95], v[192:195], v[232:235], v[92:95]
	v_mfma_f32_16x16x32_bf16 v[68:71], v[196:199], v[232:235], v[68:71]
	v_mfma_f32_16x16x32_bf16 v[76:79], v[200:203], v[232:235], v[76:79]
	ds_read_b128 v[232:235], v166 offset:14336
	ds_read_b128 v[216:219], v167 offset:6144
	v_add_u32_e32 v166, s49, v143
	s_waitcnt lgkmcnt(7)
	v_mfma_f32_16x16x32_bf16 v[48:51], v[188:191], v[220:223], v[48:51]
	v_mfma_f32_16x16x32_bf16 v[56:59], v[192:195], v[220:223], v[56:59]
	v_mfma_f32_16x16x32_bf16 v[32:35], v[196:199], v[220:223], v[32:35]
	v_mfma_f32_16x16x32_bf16 v[40:43], v[200:203], v[220:223], v[40:43]
	ds_read_b128 v[220:223], v166
	s_waitcnt lgkmcnt(6)
	v_mfma_f32_16x16x32_bf16 v[52:55], v[188:191], v[224:227], v[52:55]
	v_mfma_f32_16x16x32_bf16 v[60:63], v[192:195], v[224:227], v[60:63]
	v_mfma_f32_16x16x32_bf16 v[36:39], v[196:199], v[224:227], v[36:39]
	v_mfma_f32_16x16x32_bf16 v[44:47], v[200:203], v[224:227], v[44:47]
	ds_read_b128 v[224:227], v166 offset:2048
	s_waitcnt lgkmcnt(5)
	v_mfma_f32_16x16x32_bf16 v[16:19], v[188:191], v[228:231], v[16:19]
	v_mfma_f32_16x16x32_bf16 v[24:27], v[192:195], v[228:231], v[24:27]
	v_mfma_f32_16x16x32_bf16 v[0:3], v[196:199], v[228:231], v[0:3]
	v_mfma_f32_16x16x32_bf16 v[8:11], v[200:203], v[228:231], v[8:11]
	ds_read_b128 v[228:231], v166 offset:4096
	s_waitcnt lgkmcnt(4)
	v_mfma_f32_16x16x32_bf16 v[20:23], v[188:191], v[232:235], v[20:23]
	v_mfma_f32_16x16x32_bf16 v[28:31], v[192:195], v[232:235], v[28:31]
	v_mfma_f32_16x16x32_bf16 v[4:7], v[196:199], v[232:235], v[4:7]
	v_mfma_f32_16x16x32_bf16 v[12:15], v[200:203], v[232:235], v[12:15]
	ds_read_b128 v[232:235], v166 offset:6144
	s_waitcnt lgkmcnt(4)
	s_waitcnt lgkmcnt(3)
	v_mfma_f32_16x16x32_bf16 v[112:115], v[204:207], v[220:223], v[112:115]
	v_mfma_f32_16x16x32_bf16 v[120:123], v[208:211], v[220:223], v[120:123]
	v_mfma_f32_16x16x32_bf16 v[96:99], v[212:215], v[220:223], v[96:99]
	v_mfma_f32_16x16x32_bf16 v[104:107], v[216:219], v[220:223], v[104:107]
	ds_read_b128 v[220:223], v166 offset:8192
	s_waitcnt lgkmcnt(3)
	v_mfma_f32_16x16x32_bf16 v[116:119], v[204:207], v[224:227], v[116:119]
	v_mfma_f32_16x16x32_bf16 v[124:127], v[208:211], v[224:227], v[124:127]
	v_mfma_f32_16x16x32_bf16 v[100:103], v[212:215], v[224:227], v[100:103]
	v_mfma_f32_16x16x32_bf16 v[108:111], v[216:219], v[224:227], v[108:111]
	ds_read_b128 v[224:227], v166 offset:10240
	s_waitcnt lgkmcnt(3)
	v_mfma_f32_16x16x32_bf16 v[80:83], v[204:207], v[228:231], v[80:83]
	v_mfma_f32_16x16x32_bf16 v[88:91], v[208:211], v[228:231], v[88:91]
	v_mfma_f32_16x16x32_bf16 v[64:67], v[212:215], v[228:231], v[64:67]
	v_mfma_f32_16x16x32_bf16 v[72:75], v[216:219], v[228:231], v[72:75]
	ds_read_b128 v[228:231], v166 offset:12288
	s_waitcnt lgkmcnt(3)
	v_mfma_f32_16x16x32_bf16 v[84:87], v[204:207], v[232:235], v[84:87]
	v_mfma_f32_16x16x32_bf16 v[92:95], v[208:211], v[232:235], v[92:95]
	v_mfma_f32_16x16x32_bf16 v[68:71], v[212:215], v[232:235], v[68:71]
	v_mfma_f32_16x16x32_bf16 v[76:79], v[216:219], v[232:235], v[76:79]
	ds_read_b128 v[232:235], v166 offset:14336
	s_waitcnt lgkmcnt(3)
	v_mfma_f32_16x16x32_bf16 v[48:51], v[204:207], v[220:223], v[48:51]
	v_mfma_f32_16x16x32_bf16 v[56:59], v[208:211], v[220:223], v[56:59]
	v_mfma_f32_16x16x32_bf16 v[32:35], v[212:215], v[220:223], v[32:35]
	v_mfma_f32_16x16x32_bf16 v[40:43], v[216:219], v[220:223], v[40:43]
	s_waitcnt lgkmcnt(2)
	v_mfma_f32_16x16x32_bf16 v[52:55], v[204:207], v[224:227], v[52:55]
	v_mfma_f32_16x16x32_bf16 v[60:63], v[208:211], v[224:227], v[60:63]
	v_mfma_f32_16x16x32_bf16 v[36:39], v[212:215], v[224:227], v[36:39]
	v_mfma_f32_16x16x32_bf16 v[44:47], v[216:219], v[224:227], v[44:47]
	s_waitcnt lgkmcnt(1)
	v_mfma_f32_16x16x32_bf16 v[16:19], v[204:207], v[228:231], v[16:19]
	v_mfma_f32_16x16x32_bf16 v[24:27], v[208:211], v[228:231], v[24:27]
	v_mfma_f32_16x16x32_bf16 v[0:3], v[212:215], v[228:231], v[0:3]
	v_mfma_f32_16x16x32_bf16 v[8:11], v[216:219], v[228:231], v[8:11]
	s_waitcnt lgkmcnt(0)
	s_waitcnt vmcnt(0)
	s_barrier
	v_mfma_f32_16x16x32_bf16 v[20:23], v[204:207], v[232:235], v[20:23]
	v_mfma_f32_16x16x32_bf16 v[28:31], v[208:211], v[232:235], v[28:31]
	v_mfma_f32_16x16x32_bf16 v[4:7], v[212:215], v[232:235], v[4:7]
	v_mfma_f32_16x16x32_bf16 v[12:15], v[216:219], v[232:235], v[12:15]
	s_nop 15
	v_permlane16_swap_b32_e32 v112, v116
	v_permlane16_swap_b32_e32 v113, v117
	v_permlane16_swap_b32_e32 v114, v118
	v_permlane16_swap_b32_e32 v115, v119
	v_permlane16_swap_b32_e32 v120, v124
	v_permlane16_swap_b32_e32 v121, v125
	v_permlane16_swap_b32_e32 v122, v126
	v_permlane16_swap_b32_e32 v123, v127
	v_permlane16_swap_b32_e32 v96, v100
	v_permlane16_swap_b32_e32 v97, v101
	v_permlane16_swap_b32_e32 v98, v102
	v_permlane16_swap_b32_e32 v99, v103
	v_permlane16_swap_b32_e32 v104, v108
	v_permlane16_swap_b32_e32 v105, v109
	v_permlane16_swap_b32_e32 v106, v110
	v_permlane16_swap_b32_e32 v107, v111
	v_permlane16_swap_b32_e32 v80, v84
	v_permlane16_swap_b32_e32 v81, v85
	v_permlane16_swap_b32_e32 v82, v86
	v_permlane16_swap_b32_e32 v83, v87
	v_permlane16_swap_b32_e32 v88, v92
	v_permlane16_swap_b32_e32 v89, v93
	v_permlane16_swap_b32_e32 v90, v94
	v_permlane16_swap_b32_e32 v91, v95
	v_permlane16_swap_b32_e32 v64, v68
	v_permlane16_swap_b32_e32 v65, v69
	v_permlane16_swap_b32_e32 v66, v70
	v_permlane16_swap_b32_e32 v67, v71
	v_permlane16_swap_b32_e32 v72, v76
	v_permlane16_swap_b32_e32 v73, v77
	v_permlane16_swap_b32_e32 v74, v78
	v_permlane16_swap_b32_e32 v75, v79
	v_permlane16_swap_b32_e32 v48, v52
	v_permlane16_swap_b32_e32 v49, v53
	v_permlane16_swap_b32_e32 v50, v54
	v_permlane16_swap_b32_e32 v51, v55
	v_permlane16_swap_b32_e32 v56, v60
	v_permlane16_swap_b32_e32 v57, v61
	v_permlane16_swap_b32_e32 v58, v62
	v_permlane16_swap_b32_e32 v59, v63
	v_permlane16_swap_b32_e32 v32, v36
	v_permlane16_swap_b32_e32 v33, v37
	v_permlane16_swap_b32_e32 v34, v38
	v_permlane16_swap_b32_e32 v35, v39
	v_permlane16_swap_b32_e32 v40, v44
	v_permlane16_swap_b32_e32 v41, v45
	v_permlane16_swap_b32_e32 v42, v46
	v_permlane16_swap_b32_e32 v43, v47
	v_permlane16_swap_b32_e32 v16, v20
	v_permlane16_swap_b32_e32 v17, v21
	v_permlane16_swap_b32_e32 v18, v22
	v_permlane16_swap_b32_e32 v19, v23
	v_permlane16_swap_b32_e32 v24, v28
	v_permlane16_swap_b32_e32 v25, v29
	v_permlane16_swap_b32_e32 v26, v30
	v_permlane16_swap_b32_e32 v27, v31
	v_permlane16_swap_b32_e32 v0, v4
	v_permlane16_swap_b32_e32 v1, v5
	v_permlane16_swap_b32_e32 v2, v6
	v_permlane16_swap_b32_e32 v3, v7
	v_permlane16_swap_b32_e32 v8, v12
	v_permlane16_swap_b32_e32 v9, v13
	v_permlane16_swap_b32_e32 v10, v14
	v_permlane16_swap_b32_e32 v11, v15
	v_permlane32_swap_b32_e32 v112, v116
	v_permlane32_swap_b32_e32 v113, v117
	v_permlane32_swap_b32_e32 v114, v118
	v_permlane32_swap_b32_e32 v115, v119
	v_permlane32_swap_b32_e32 v120, v124
	v_permlane32_swap_b32_e32 v121, v125
	v_permlane32_swap_b32_e32 v122, v126
	v_permlane32_swap_b32_e32 v123, v127
	v_permlane32_swap_b32_e32 v96, v100
	v_permlane32_swap_b32_e32 v97, v101
	v_permlane32_swap_b32_e32 v98, v102
	v_permlane32_swap_b32_e32 v99, v103
	v_permlane32_swap_b32_e32 v104, v108
	v_permlane32_swap_b32_e32 v105, v109
	v_permlane32_swap_b32_e32 v106, v110
	v_permlane32_swap_b32_e32 v107, v111
	v_permlane32_swap_b32_e32 v80, v84
	v_permlane32_swap_b32_e32 v81, v85
	v_permlane32_swap_b32_e32 v82, v86
	v_permlane32_swap_b32_e32 v83, v87
	v_permlane32_swap_b32_e32 v88, v92
	v_permlane32_swap_b32_e32 v89, v93
	v_permlane32_swap_b32_e32 v90, v94
	v_permlane32_swap_b32_e32 v91, v95
	v_permlane32_swap_b32_e32 v64, v68
	v_permlane32_swap_b32_e32 v65, v69
	v_permlane32_swap_b32_e32 v66, v70
	v_permlane32_swap_b32_e32 v67, v71
	v_permlane32_swap_b32_e32 v72, v76
	v_permlane32_swap_b32_e32 v73, v77
	v_permlane32_swap_b32_e32 v74, v78
	v_permlane32_swap_b32_e32 v75, v79
	v_permlane32_swap_b32_e32 v48, v52
	v_permlane32_swap_b32_e32 v49, v53
	v_permlane32_swap_b32_e32 v50, v54
	v_permlane32_swap_b32_e32 v51, v55
	v_permlane32_swap_b32_e32 v56, v60
	v_permlane32_swap_b32_e32 v57, v61
	v_permlane32_swap_b32_e32 v58, v62
	v_permlane32_swap_b32_e32 v59, v63
	v_permlane32_swap_b32_e32 v32, v36
	v_permlane32_swap_b32_e32 v33, v37
	v_permlane32_swap_b32_e32 v34, v38
	v_permlane32_swap_b32_e32 v35, v39
	v_permlane32_swap_b32_e32 v40, v44
	v_permlane32_swap_b32_e32 v41, v45
	v_permlane32_swap_b32_e32 v42, v46
	v_permlane32_swap_b32_e32 v43, v47
	v_permlane32_swap_b32_e32 v16, v20
	v_permlane32_swap_b32_e32 v17, v21
	v_permlane32_swap_b32_e32 v18, v22
	v_permlane32_swap_b32_e32 v19, v23
	v_permlane32_swap_b32_e32 v24, v28
	v_permlane32_swap_b32_e32 v25, v29
	v_permlane32_swap_b32_e32 v26, v30
	v_permlane32_swap_b32_e32 v27, v31
	v_permlane32_swap_b32_e32 v0, v4
	v_permlane32_swap_b32_e32 v1, v5
	v_permlane32_swap_b32_e32 v2, v6
	v_permlane32_swap_b32_e32 v3, v7
	v_permlane32_swap_b32_e32 v8, v12
	v_permlane32_swap_b32_e32 v9, v13
	v_permlane32_swap_b32_e32 v10, v14
	v_permlane32_swap_b32_e32 v11, v15
	s_nop 1
	s_branch .LBB0_163

.Lg163_loop:
	s_add_u32 s51, s50, 0x10000
	s_sub_u32 s53, s51, 0x28000
	s_cmp_ge_u32 s51, 0x28000
	s_cselect_b32 s51, s53, s51
	s_add_u32 s52, s49, 0x20000
	s_sub_u32 s53, s52, 0x28000
	s_cmp_ge_u32 s52, 0x28000
	s_cselect_b32 s52, s53, s52
	v_add_u32_e32 v246, s50, v244
	s_waitcnt lgkmcnt(4)
	s_waitcnt lgkmcnt(3)
	v_mfma_f32_16x16x32_bf16 v[112:115], v[192:195], v[224:227], v[112:115]
	v_mfma_f32_16x16x32_bf16 v[120:123], v[196:199], v[224:227], v[120:123]
	v_mfma_f32_16x16x32_bf16 v[96:99], v[200:203], v[224:227], v[96:99]
	v_mfma_f32_16x16x32_bf16 v[104:107], v[204:207], v[224:227], v[104:107]
	s_add_u32 m0, s51, s48
	s_nop 0
	global_load_lds_dwordx4 v248, s[64:65]
	s_add_u32 s64, s64, 0x80
	s_addc_u32 s65, s65, 0
	s_add_u32 s53, s51, s48
	s_add_u32 m0, s53, 0x2000
	s_nop 0
	global_load_lds_dwordx4 v248, s[66:67]
	s_add_u32 s66, s66, 0x80
	s_addc_u32 s67, s67, 0
	ds_read_b128 v[224:227], v245 offset:8192
	ds_read_b128 v[208:211], v246
	s_waitcnt lgkmcnt(4)
	v_mfma_f32_16x16x32_bf16 v[116:119], v[192:195], v[228:231], v[116:119]
	v_mfma_f32_16x16x32_bf16 v[124:127], v[196:199], v[228:231], v[124:127]
	v_mfma_f32_16x16x32_bf16 v[100:103], v[200:203], v[228:231], v[100:103]
	v_mfma_f32_16x16x32_bf16 v[108:111], v[204:207], v[228:231], v[108:111]
	s_add_u32 s53, s51, s48
	s_add_u32 m0, s53, 0x4000
	s_nop 0
	global_load_lds_dwordx4 v248, s[68:69]
	s_add_u32 s68, s68, 0x80
	s_addc_u32 s69, s69, 0
	s_add_u32 s53, s51, s48
	s_add_u32 m0, s53, 0x6000
	s_nop 0
	global_load_lds_dwordx4 v248, s[70:71]
	s_add_u32 s70, s70, 0x80
	s_addc_u32 s71, s71, 0
	ds_read_b128 v[228:231], v245 offset:10240
	ds_read_b128 v[212:215], v246 offset:2048
	s_waitcnt lgkmcnt(5)
	v_mfma_f32_16x16x32_bf16 v[80:83], v[192:195], v[232:235], v[80:83]
	v_mfma_f32_16x16x32_bf16 v[88:91], v[196:199], v[232:235], v[88:91]
	v_mfma_f32_16x16x32_bf16 v[64:67], v[200:203], v[232:235], v[64:67]
	v_mfma_f32_16x16x32_bf16 v[72:75], v[204:207], v[232:235], v[72:75]
	ds_read_b128 v[232:235], v245 offset:12288
	ds_read_b128 v[216:219], v246 offset:4096
	s_waitcnt lgkmcnt(6)
	v_mfma_f32_16x16x32_bf16 v[84:87], v[192:195], v[236:239], v[84:87]
	v_mfma_f32_16x16x32_bf16 v[92:95], v[196:199], v[236:239], v[92:95]
	v_mfma_f32_16x16x32_bf16 v[68:71], v[200:203], v[236:239], v[68:71]
	v_mfma_f32_16x16x32_bf16 v[76:79], v[204:207], v[236:239], v[76:79]
	ds_read_b128 v[236:239], v245 offset:14336
	ds_read_b128 v[220:223], v246 offset:6144
	v_add_u32_e32 v245, s49, v241
	s_waitcnt lgkmcnt(7)
	v_mfma_f32_16x16x32_bf16 v[48:51], v[192:195], v[224:227], v[48:51]
	v_mfma_f32_16x16x32_bf16 v[56:59], v[196:199], v[224:227], v[56:59]
	v_mfma_f32_16x16x32_bf16 v[32:35], v[200:203], v[224:227], v[32:35]
	v_mfma_f32_16x16x32_bf16 v[40:43], v[204:207], v[224:227], v[40:43]
	ds_read_b128 v[224:227], v245
	s_waitcnt lgkmcnt(6)
	v_mfma_f32_16x16x32_bf16 v[52:55], v[192:195], v[228:231], v[52:55]
	v_mfma_f32_16x16x32_bf16 v[60:63], v[196:199], v[228:231], v[60:63]
	v_mfma_f32_16x16x32_bf16 v[36:39], v[200:203], v[228:231], v[36:39]
	v_mfma_f32_16x16x32_bf16 v[44:47], v[204:207], v[228:231], v[44:47]
	ds_read_b128 v[228:231], v245 offset:2048
	s_waitcnt lgkmcnt(5)
	v_mfma_f32_16x16x32_bf16 v[16:19], v[192:195], v[232:235], v[16:19]
	v_mfma_f32_16x16x32_bf16 v[24:27], v[196:199], v[232:235], v[24:27]
	v_mfma_f32_16x16x32_bf16 v[0:3], v[200:203], v[232:235], v[0:3]
	v_mfma_f32_16x16x32_bf16 v[8:11], v[204:207], v[232:235], v[8:11]
	ds_read_b128 v[232:235], v245 offset:4096
	s_waitcnt lgkmcnt(4)
	v_mfma_f32_16x16x32_bf16 v[20:23], v[192:195], v[236:239], v[20:23]
	v_mfma_f32_16x16x32_bf16 v[28:31], v[196:199], v[236:239], v[28:31]
	v_mfma_f32_16x16x32_bf16 v[4:7], v[200:203], v[236:239], v[4:7]
	v_mfma_f32_16x16x32_bf16 v[12:15], v[204:207], v[236:239], v[12:15]
	ds_read_b128 v[236:239], v245 offset:6144
	s_waitcnt lgkmcnt(4)
	s_waitcnt lgkmcnt(3)
	v_mfma_f32_16x16x32_bf16 v[112:115], v[208:211], v[224:227], v[112:115]
	v_mfma_f32_16x16x32_bf16 v[120:123], v[212:215], v[224:227], v[120:123]
	v_mfma_f32_16x16x32_bf16 v[96:99], v[216:219], v[224:227], v[96:99]
	v_mfma_f32_16x16x32_bf16 v[104:107], v[220:223], v[224:227], v[104:107]
	ds_read_b128 v[224:227], v245 offset:8192
	s_waitcnt lgkmcnt(3)
	v_mfma_f32_16x16x32_bf16 v[116:119], v[208:211], v[228:231], v[116:119]
	v_mfma_f32_16x16x32_bf16 v[124:127], v[212:215], v[228:231], v[124:127]
	v_mfma_f32_16x16x32_bf16 v[100:103], v[216:219], v[228:231], v[100:103]
	v_mfma_f32_16x16x32_bf16 v[108:111], v[220:223], v[228:231], v[108:111]
	ds_read_b128 v[228:231], v245 offset:10240
	s_waitcnt lgkmcnt(3)
	v_mfma_f32_16x16x32_bf16 v[80:83], v[208:211], v[232:235], v[80:83]
	v_mfma_f32_16x16x32_bf16 v[88:91], v[212:215], v[232:235], v[88:91]
	v_mfma_f32_16x16x32_bf16 v[64:67], v[216:219], v[232:235], v[64:67]
	v_mfma_f32_16x16x32_bf16 v[72:75], v[220:223], v[232:235], v[72:75]
	ds_read_b128 v[232:235], v245 offset:12288
	s_waitcnt lgkmcnt(3)
	v_mfma_f32_16x16x32_bf16 v[84:87], v[208:211], v[236:239], v[84:87]
	v_mfma_f32_16x16x32_bf16 v[92:95], v[212:215], v[236:239], v[92:95]
	v_mfma_f32_16x16x32_bf16 v[68:71], v[216:219], v[236:239], v[68:71]
	v_mfma_f32_16x16x32_bf16 v[76:79], v[220:223], v[236:239], v[76:79]
	ds_read_b128 v[236:239], v245 offset:14336
	s_waitcnt lgkmcnt(3)
	v_mfma_f32_16x16x32_bf16 v[48:51], v[208:211], v[224:227], v[48:51]
	v_mfma_f32_16x16x32_bf16 v[56:59], v[212:215], v[224:227], v[56:59]
	v_mfma_f32_16x16x32_bf16 v[32:35], v[216:219], v[224:227], v[32:35]
	v_mfma_f32_16x16x32_bf16 v[40:43], v[220:223], v[224:227], v[40:43]
	s_add_u32 m0, s52, s48
	s_nop 0
	global_load_lds_dwordx4 v247, s[56:57]
	s_add_u32 s56, s56, 0x80
	s_addc_u32 s57, s57, 0
	s_add_u32 s53, s52, s48
	s_add_u32 m0, s53, 0x2000
	s_nop 0
	global_load_lds_dwordx4 v247, s[58:59]
	s_add_u32 s58, s58, 0x80
	s_addc_u32 s59, s59, 0
	s_waitcnt lgkmcnt(2)
	v_mfma_f32_16x16x32_bf16 v[52:55], v[208:211], v[228:231], v[52:55]
	v_mfma_f32_16x16x32_bf16 v[60:63], v[212:215], v[228:231], v[60:63]
	v_mfma_f32_16x16x32_bf16 v[36:39], v[216:219], v[228:231], v[36:39]
	v_mfma_f32_16x16x32_bf16 v[44:47], v[220:223], v[228:231], v[44:47]
	s_add_u32 s53, s52, s48
	s_add_u32 m0, s53, 0x4000
	s_nop 0
	global_load_lds_dwordx4 v247, s[60:61]
	s_add_u32 s60, s60, 0x80
	s_addc_u32 s61, s61, 0
	s_add_u32 s53, s52, s48
	s_add_u32 m0, s53, 0x6000
	s_nop 0
	global_load_lds_dwordx4 v247, s[62:63]
	s_add_u32 s62, s62, 0x80
	s_addc_u32 s63, s63, 0
	s_waitcnt lgkmcnt(1)
	v_mfma_f32_16x16x32_bf16 v[16:19], v[208:211], v[232:235], v[16:19]
	v_mfma_f32_16x16x32_bf16 v[24:27], v[212:215], v[232:235], v[24:27]
	v_mfma_f32_16x16x32_bf16 v[0:3], v[216:219], v[232:235], v[0:3]
	v_mfma_f32_16x16x32_bf16 v[8:11], v[220:223], v[232:235], v[8:11]
	s_waitcnt lgkmcnt(0)
	s_add_u32 s28, s28, 0x80
	s_addc_u32 s29, s29, 0
	s_add_u32 s49, s49, 0x10000
	s_sub_u32 s53, s49, 0x28000
	s_cmp_ge_u32 s49, 0x28000
	s_cselect_b32 s49, s53, s49
	s_mov_b32 s50, s51
	s_waitcnt vmcnt(4)
	s_barrier
	v_add_u32_e32 v246, s50, v243
	v_add_u32_e32 v245, s49, v240
	ds_read_b128 v[192:195], v246
	ds_read_b128 v[196:199], v246 offset:2048
	ds_read_b128 v[200:203], v246 offset:4096
	ds_read_b128 v[204:207], v246 offset:6144
	ds_read_b128 v[224:227], v245
	ds_read_b128 v[228:231], v245 offset:2048
	ds_read_b128 v[232:235], v245 offset:4096
	v_mfma_f32_16x16x32_bf16 v[20:23], v[208:211], v[236:239], v[20:23]
	v_mfma_f32_16x16x32_bf16 v[28:31], v[212:215], v[236:239], v[28:31]
	v_mfma_f32_16x16x32_bf16 v[4:7], v[216:219], v[236:239], v[4:7]
	v_mfma_f32_16x16x32_bf16 v[12:15], v[220:223], v[236:239], v[12:15]
	ds_read_b128 v[236:239], v245 offset:6144
	s_cmpk_lg_i32 s28, 0xf00
	s_cbranch_scc1 .Lg163_loop
	s_add_u32 s51, s50, 0x10000
	s_sub_u32 s53, s51, 0x28000
	s_cmp_ge_u32 s51, 0x28000
	s_cselect_b32 s51, s53, s51
	v_add_u32_e32 v246, s50, v244
	s_waitcnt lgkmcnt(4)
	s_waitcnt lgkmcnt(3)
	v_mfma_f32_16x16x32_bf16 v[112:115], v[192:195], v[224:227], v[112:115]
	v_mfma_f32_16x16x32_bf16 v[120:123], v[196:199], v[224:227], v[120:123]
	v_mfma_f32_16x16x32_bf16 v[96:99], v[200:203], v[224:227], v[96:99]
	v_mfma_f32_16x16x32_bf16 v[104:107], v[204:207], v[224:227], v[104:107]
	s_add_u32 m0, s51, s48
	s_nop 0
	global_load_lds_dwordx4 v248, s[64:65]
	s_add_u32 s64, s64, 0x80
	s_addc_u32 s65, s65, 0
	s_add_u32 s53, s51, s48
	s_add_u32 m0, s53, 0x2000
	s_nop 0
	global_load_lds_dwordx4 v248, s[66:67]
	s_add_u32 s66, s66, 0x80
	s_addc_u32 s67, s67, 0
	ds_read_b128 v[224:227], v245 offset:8192
	ds_read_b128 v[208:211], v246
	s_waitcnt lgkmcnt(4)
	v_mfma_f32_16x16x32_bf16 v[116:119], v[192:195], v[228:231], v[116:119]
	v_mfma_f32_16x16x32_bf16 v[124:127], v[196:199], v[228:231], v[124:127]
	v_mfma_f32_16x16x32_bf16 v[100:103], v[200:203], v[228:231], v[100:103]
	v_mfma_f32_16x16x32_bf16 v[108:111], v[204:207], v[228:231], v[108:111]
	s_add_u32 s53, s51, s48
	s_add_u32 m0, s53, 0x4000
	s_nop 0
	global_load_lds_dwordx4 v248, s[68:69]
	s_add_u32 s68, s68, 0x80
	s_addc_u32 s69, s69, 0
	s_add_u32 s53, s51, s48
	s_add_u32 m0, s53, 0x6000
	s_nop 0
	global_load_lds_dwordx4 v248, s[70:71]
	s_add_u32 s70, s70, 0x80
	s_addc_u32 s71, s71, 0
	ds_read_b128 v[228:231], v245 offset:10240
	ds_read_b128 v[212:215], v246 offset:2048
	s_waitcnt lgkmcnt(5)
	v_mfma_f32_16x16x32_bf16 v[80:83], v[192:195], v[232:235], v[80:83]
	v_mfma_f32_16x16x32_bf16 v[88:91], v[196:199], v[232:235], v[88:91]
	v_mfma_f32_16x16x32_bf16 v[64:67], v[200:203], v[232:235], v[64:67]
	v_mfma_f32_16x16x32_bf16 v[72:75], v[204:207], v[232:235], v[72:75]
	ds_read_b128 v[232:235], v245 offset:12288
	ds_read_b128 v[216:219], v246 offset:4096
	s_waitcnt lgkmcnt(6)
	v_mfma_f32_16x16x32_bf16 v[84:87], v[192:195], v[236:239], v[84:87]
	v_mfma_f32_16x16x32_bf16 v[92:95], v[196:199], v[236:239], v[92:95]
	v_mfma_f32_16x16x32_bf16 v[68:71], v[200:203], v[236:239], v[68:71]
	v_mfma_f32_16x16x32_bf16 v[76:79], v[204:207], v[236:239], v[76:79]
	ds_read_b128 v[236:239], v245 offset:14336
	ds_read_b128 v[220:223], v246 offset:6144
	v_add_u32_e32 v245, s49, v241
	s_waitcnt lgkmcnt(7)
	v_mfma_f32_16x16x32_bf16 v[48:51], v[192:195], v[224:227], v[48:51]
	v_mfma_f32_16x16x32_bf16 v[56:59], v[196:199], v[224:227], v[56:59]
	v_mfma_f32_16x16x32_bf16 v[32:35], v[200:203], v[224:227], v[32:35]
	v_mfma_f32_16x16x32_bf16 v[40:43], v[204:207], v[224:227], v[40:43]
	ds_read_b128 v[224:227], v245
	s_waitcnt lgkmcnt(6)
	v_mfma_f32_16x16x32_bf16 v[52:55], v[192:195], v[228:231], v[52:55]
	v_mfma_f32_16x16x32_bf16 v[60:63], v[196:199], v[228:231], v[60:63]
	v_mfma_f32_16x16x32_bf16 v[36:39], v[200:203], v[228:231], v[36:39]
	v_mfma_f32_16x16x32_bf16 v[44:47], v[204:207], v[228:231], v[44:47]
	ds_read_b128 v[228:231], v245 offset:2048
	s_waitcnt lgkmcnt(5)
	v_mfma_f32_16x16x32_bf16 v[16:19], v[192:195], v[232:235], v[16:19]
	v_mfma_f32_16x16x32_bf16 v[24:27], v[196:199], v[232:235], v[24:27]
	v_mfma_f32_16x16x32_bf16 v[0:3], v[200:203], v[232:235], v[0:3]
	v_mfma_f32_16x16x32_bf16 v[8:11], v[204:207], v[232:235], v[8:11]
	ds_read_b128 v[232:235], v245 offset:4096
	s_waitcnt lgkmcnt(4)
	v_mfma_f32_16x16x32_bf16 v[20:23], v[192:195], v[236:239], v[20:23]
	v_mfma_f32_16x16x32_bf16 v[28:31], v[196:199], v[236:239], v[28:31]
	v_mfma_f32_16x16x32_bf16 v[4:7], v[200:203], v[236:239], v[4:7]
	v_mfma_f32_16x16x32_bf16 v[12:15], v[204:207], v[236:239], v[12:15]
	ds_read_b128 v[236:239], v245 offset:6144
	s_waitcnt lgkmcnt(4)
	s_waitcnt lgkmcnt(3)
	v_mfma_f32_16x16x32_bf16 v[112:115], v[208:211], v[224:227], v[112:115]
	v_mfma_f32_16x16x32_bf16 v[120:123], v[212:215], v[224:227], v[120:123]
	v_mfma_f32_16x16x32_bf16 v[96:99], v[216:219], v[224:227], v[96:99]
	v_mfma_f32_16x16x32_bf16 v[104:107], v[220:223], v[224:227], v[104:107]
	ds_read_b128 v[224:227], v245 offset:8192
	s_waitcnt lgkmcnt(3)
	v_mfma_f32_16x16x32_bf16 v[116:119], v[208:211], v[228:231], v[116:119]
	v_mfma_f32_16x16x32_bf16 v[124:127], v[212:215], v[228:231], v[124:127]
	v_mfma_f32_16x16x32_bf16 v[100:103], v[216:219], v[228:231], v[100:103]
	v_mfma_f32_16x16x32_bf16 v[108:111], v[220:223], v[228:231], v[108:111]
	ds_read_b128 v[228:231], v245 offset:10240
	s_waitcnt lgkmcnt(3)
	v_mfma_f32_16x16x32_bf16 v[80:83], v[208:211], v[232:235], v[80:83]
	v_mfma_f32_16x16x32_bf16 v[88:91], v[212:215], v[232:235], v[88:91]
	v_mfma_f32_16x16x32_bf16 v[64:67], v[216:219], v[232:235], v[64:67]
	v_mfma_f32_16x16x32_bf16 v[72:75], v[220:223], v[232:235], v[72:75]
	ds_read_b128 v[232:235], v245 offset:12288
	s_waitcnt lgkmcnt(3)
	v_mfma_f32_16x16x32_bf16 v[84:87], v[208:211], v[236:239], v[84:87]
	v_mfma_f32_16x16x32_bf16 v[92:95], v[212:215], v[236:239], v[92:95]
	v_mfma_f32_16x16x32_bf16 v[68:71], v[216:219], v[236:239], v[68:71]
	v_mfma_f32_16x16x32_bf16 v[76:79], v[220:223], v[236:239], v[76:79]
	ds_read_b128 v[236:239], v245 offset:14336
	s_waitcnt lgkmcnt(3)
	v_mfma_f32_16x16x32_bf16 v[48:51], v[208:211], v[224:227], v[48:51]
	v_mfma_f32_16x16x32_bf16 v[56:59], v[212:215], v[224:227], v[56:59]
	v_mfma_f32_16x16x32_bf16 v[32:35], v[216:219], v[224:227], v[32:35]
	v_mfma_f32_16x16x32_bf16 v[40:43], v[220:223], v[224:227], v[40:43]
	s_waitcnt lgkmcnt(2)
	v_mfma_f32_16x16x32_bf16 v[52:55], v[208:211], v[228:231], v[52:55]
	v_mfma_f32_16x16x32_bf16 v[60:63], v[212:215], v[228:231], v[60:63]
	v_mfma_f32_16x16x32_bf16 v[36:39], v[216:219], v[228:231], v[36:39]
	v_mfma_f32_16x16x32_bf16 v[44:47], v[220:223], v[228:231], v[44:47]
	s_waitcnt lgkmcnt(1)
	v_mfma_f32_16x16x32_bf16 v[16:19], v[208:211], v[232:235], v[16:19]
	v_mfma_f32_16x16x32_bf16 v[24:27], v[212:215], v[232:235], v[24:27]
	v_mfma_f32_16x16x32_bf16 v[0:3], v[216:219], v[232:235], v[0:3]
	v_mfma_f32_16x16x32_bf16 v[8:11], v[220:223], v[232:235], v[8:11]
	s_waitcnt lgkmcnt(0)
	s_add_u32 s28, s28, 0x80
	s_addc_u32 s29, s29, 0
	s_add_u32 s49, s49, 0x10000
	s_sub_u32 s53, s49, 0x28000
	s_cmp_ge_u32 s49, 0x28000
	s_cselect_b32 s49, s53, s49
	s_mov_b32 s50, s51
	s_waitcnt vmcnt(0)
	s_barrier
	v_add_u32_e32 v246, s50, v243
	v_add_u32_e32 v245, s49, v240
	ds_read_b128 v[192:195], v246
	ds_read_b128 v[196:199], v246 offset:2048
	ds_read_b128 v[200:203], v246 offset:4096
	ds_read_b128 v[204:207], v246 offset:6144
	ds_read_b128 v[224:227], v245
	ds_read_b128 v[228:231], v245 offset:2048
	ds_read_b128 v[232:235], v245 offset:4096
	v_mfma_f32_16x16x32_bf16 v[20:23], v[208:211], v[236:239], v[20:23]
	v_mfma_f32_16x16x32_bf16 v[28:31], v[212:215], v[236:239], v[28:31]
	v_mfma_f32_16x16x32_bf16 v[4:7], v[216:219], v[236:239], v[4:7]
	v_mfma_f32_16x16x32_bf16 v[12:15], v[220:223], v[236:239], v[12:15]
	ds_read_b128 v[236:239], v245 offset:6144
	v_add_u32_e32 v246, s50, v244
	s_waitcnt lgkmcnt(4)
	s_waitcnt lgkmcnt(3)
	v_mfma_f32_16x16x32_bf16 v[112:115], v[192:195], v[224:227], v[112:115]
	v_mfma_f32_16x16x32_bf16 v[120:123], v[196:199], v[224:227], v[120:123]
	v_mfma_f32_16x16x32_bf16 v[96:99], v[200:203], v[224:227], v[96:99]
	v_mfma_f32_16x16x32_bf16 v[104:107], v[204:207], v[224:227], v[104:107]
	ds_read_b128 v[224:227], v245 offset:8192
	ds_read_b128 v[208:211], v246
	s_waitcnt lgkmcnt(4)
	v_mfma_f32_16x16x32_bf16 v[116:119], v[192:195], v[228:231], v[116:119]
	v_mfma_f32_16x16x32_bf16 v[124:127], v[196:199], v[228:231], v[124:127]
	v_mfma_f32_16x16x32_bf16 v[100:103], v[200:203], v[228:231], v[100:103]
	v_mfma_f32_16x16x32_bf16 v[108:111], v[204:207], v[228:231], v[108:111]
	ds_read_b128 v[228:231], v245 offset:10240
	ds_read_b128 v[212:215], v246 offset:2048
	s_waitcnt lgkmcnt(5)
	v_mfma_f32_16x16x32_bf16 v[80:83], v[192:195], v[232:235], v[80:83]
	v_mfma_f32_16x16x32_bf16 v[88:91], v[196:199], v[232:235], v[88:91]
	v_mfma_f32_16x16x32_bf16 v[64:67], v[200:203], v[232:235], v[64:67]
	v_mfma_f32_16x16x32_bf16 v[72:75], v[204:207], v[232:235], v[72:75]
	ds_read_b128 v[232:235], v245 offset:12288
	ds_read_b128 v[216:219], v246 offset:4096
	s_waitcnt lgkmcnt(6)
	v_mfma_f32_16x16x32_bf16 v[84:87], v[192:195], v[236:239], v[84:87]
	v_mfma_f32_16x16x32_bf16 v[92:95], v[196:199], v[236:239], v[92:95]
	v_mfma_f32_16x16x32_bf16 v[68:71], v[200:203], v[236:239], v[68:71]
	v_mfma_f32_16x16x32_bf16 v[76:79], v[204:207], v[236:239], v[76:79]
	ds_read_b128 v[236:239], v245 offset:14336
	ds_read_b128 v[220:223], v246 offset:6144
	v_add_u32_e32 v245, s49, v241
	s_waitcnt lgkmcnt(7)
	v_mfma_f32_16x16x32_bf16 v[48:51], v[192:195], v[224:227], v[48:51]
	v_mfma_f32_16x16x32_bf16 v[56:59], v[196:199], v[224:227], v[56:59]
	v_mfma_f32_16x16x32_bf16 v[32:35], v[200:203], v[224:227], v[32:35]
	v_mfma_f32_16x16x32_bf16 v[40:43], v[204:207], v[224:227], v[40:43]
	ds_read_b128 v[224:227], v245
	s_waitcnt lgkmcnt(6)
	v_mfma_f32_16x16x32_bf16 v[52:55], v[192:195], v[228:231], v[52:55]
	v_mfma_f32_16x16x32_bf16 v[60:63], v[196:199], v[228:231], v[60:63]
	v_mfma_f32_16x16x32_bf16 v[36:39], v[200:203], v[228:231], v[36:39]
	v_mfma_f32_16x16x32_bf16 v[44:47], v[204:207], v[228:231], v[44:47]
	ds_read_b128 v[228:231], v245 offset:2048
	s_waitcnt lgkmcnt(5)
	v_mfma_f32_16x16x32_bf16 v[16:19], v[192:195], v[232:235], v[16:19]
	v_mfma_f32_16x16x32_bf16 v[24:27], v[196:199], v[232:235], v[24:27]
	v_mfma_f32_16x16x32_bf16 v[0:3], v[200:203], v[232:235], v[0:3]
	v_mfma_f32_16x16x32_bf16 v[8:11], v[204:207], v[232:235], v[8:11]
	ds_read_b128 v[232:235], v245 offset:4096
	s_waitcnt lgkmcnt(4)
	v_mfma_f32_16x16x32_bf16 v[20:23], v[192:195], v[236:239], v[20:23]
	v_mfma_f32_16x16x32_bf16 v[28:31], v[196:199], v[236:239], v[28:31]
	v_mfma_f32_16x16x32_bf16 v[4:7], v[200:203], v[236:239], v[4:7]
	v_mfma_f32_16x16x32_bf16 v[12:15], v[204:207], v[236:239], v[12:15]
	ds_read_b128 v[236:239], v245 offset:6144
	s_waitcnt lgkmcnt(4)
	s_waitcnt lgkmcnt(3)
	v_mfma_f32_16x16x32_bf16 v[112:115], v[208:211], v[224:227], v[112:115]
	v_mfma_f32_16x16x32_bf16 v[120:123], v[212:215], v[224:227], v[120:123]
	v_mfma_f32_16x16x32_bf16 v[96:99], v[216:219], v[224:227], v[96:99]
	v_mfma_f32_16x16x32_bf16 v[104:107], v[220:223], v[224:227], v[104:107]
	ds_read_b128 v[224:227], v245 offset:8192
	s_waitcnt lgkmcnt(3)
	v_mfma_f32_16x16x32_bf16 v[116:119], v[208:211], v[228:231], v[116:119]
	v_mfma_f32_16x16x32_bf16 v[124:127], v[212:215], v[228:231], v[124:127]
	v_mfma_f32_16x16x32_bf16 v[100:103], v[216:219], v[228:231], v[100:103]
	v_mfma_f32_16x16x32_bf16 v[108:111], v[220:223], v[228:231], v[108:111]
	ds_read_b128 v[228:231], v245 offset:10240
	s_waitcnt lgkmcnt(3)
	v_mfma_f32_16x16x32_bf16 v[80:83], v[208:211], v[232:235], v[80:83]
	v_mfma_f32_16x16x32_bf16 v[88:91], v[212:215], v[232:235], v[88:91]
	v_mfma_f32_16x16x32_bf16 v[64:67], v[216:219], v[232:235], v[64:67]
	v_mfma_f32_16x16x32_bf16 v[72:75], v[220:223], v[232:235], v[72:75]
	ds_read_b128 v[232:235], v245 offset:12288
	s_waitcnt lgkmcnt(3)
	v_mfma_f32_16x16x32_bf16 v[84:87], v[208:211], v[236:239], v[84:87]
	v_mfma_f32_16x16x32_bf16 v[92:95], v[212:215], v[236:239], v[92:95]
	v_mfma_f32_16x16x32_bf16 v[68:71], v[216:219], v[236:239], v[68:71]
	v_mfma_f32_16x16x32_bf16 v[76:79], v[220:223], v[236:239], v[76:79]
	ds_read_b128 v[236:239], v245 offset:14336
	s_waitcnt lgkmcnt(3)
	v_mfma_f32_16x16x32_bf16 v[48:51], v[208:211], v[224:227], v[48:51]
	v_mfma_f32_16x16x32_bf16 v[56:59], v[212:215], v[224:227], v[56:59]
	v_mfma_f32_16x16x32_bf16 v[32:35], v[216:219], v[224:227], v[32:35]
	v_mfma_f32_16x16x32_bf16 v[40:43], v[220:223], v[224:227], v[40:43]
	s_waitcnt lgkmcnt(2)
	v_mfma_f32_16x16x32_bf16 v[52:55], v[208:211], v[228:231], v[52:55]
	v_mfma_f32_16x16x32_bf16 v[60:63], v[212:215], v[228:231], v[60:63]
	v_mfma_f32_16x16x32_bf16 v[36:39], v[216:219], v[228:231], v[36:39]
	v_mfma_f32_16x16x32_bf16 v[44:47], v[220:223], v[228:231], v[44:47]
	s_waitcnt lgkmcnt(1)
	v_mfma_f32_16x16x32_bf16 v[16:19], v[208:211], v[232:235], v[16:19]
	v_mfma_f32_16x16x32_bf16 v[24:27], v[212:215], v[232:235], v[24:27]
	v_mfma_f32_16x16x32_bf16 v[0:3], v[216:219], v[232:235], v[0:3]
	v_mfma_f32_16x16x32_bf16 v[8:11], v[220:223], v[232:235], v[8:11]
	s_waitcnt lgkmcnt(0)
	s_waitcnt vmcnt(0)
	s_barrier
	v_mfma_f32_16x16x32_bf16 v[20:23], v[208:211], v[236:239], v[20:23]
	v_mfma_f32_16x16x32_bf16 v[28:31], v[212:215], v[236:239], v[28:31]
	v_mfma_f32_16x16x32_bf16 v[4:7], v[216:219], v[236:239], v[4:7]
	v_mfma_f32_16x16x32_bf16 v[12:15], v[220:223], v[236:239], v[12:15]
	s_nop 15
	v_permlane16_swap_b32_e32 v112, v116
	v_permlane16_swap_b32_e32 v113, v117
	v_permlane16_swap_b32_e32 v114, v118
	v_permlane16_swap_b32_e32 v115, v119
	v_permlane16_swap_b32_e32 v120, v124
	v_permlane16_swap_b32_e32 v121, v125
	v_permlane16_swap_b32_e32 v122, v126
	v_permlane16_swap_b32_e32 v123, v127
	v_permlane16_swap_b32_e32 v96, v100
	v_permlane16_swap_b32_e32 v97, v101
	v_permlane16_swap_b32_e32 v98, v102
	v_permlane16_swap_b32_e32 v99, v103
	v_permlane16_swap_b32_e32 v104, v108
	v_permlane16_swap_b32_e32 v105, v109
	v_permlane16_swap_b32_e32 v106, v110
	v_permlane16_swap_b32_e32 v107, v111
	v_permlane16_swap_b32_e32 v80, v84
	v_permlane16_swap_b32_e32 v81, v85
	v_permlane16_swap_b32_e32 v82, v86
	v_permlane16_swap_b32_e32 v83, v87
	v_permlane16_swap_b32_e32 v88, v92
	v_permlane16_swap_b32_e32 v89, v93
	v_permlane16_swap_b32_e32 v90, v94
	v_permlane16_swap_b32_e32 v91, v95
	v_permlane16_swap_b32_e32 v64, v68
	v_permlane16_swap_b32_e32 v65, v69
	v_permlane16_swap_b32_e32 v66, v70
	v_permlane16_swap_b32_e32 v67, v71
	v_permlane16_swap_b32_e32 v72, v76
	v_permlane16_swap_b32_e32 v73, v77
	v_permlane16_swap_b32_e32 v74, v78
	v_permlane16_swap_b32_e32 v75, v79
	v_permlane16_swap_b32_e32 v48, v52
	v_permlane16_swap_b32_e32 v49, v53
	v_permlane16_swap_b32_e32 v50, v54
	v_permlane16_swap_b32_e32 v51, v55
	v_permlane16_swap_b32_e32 v56, v60
	v_permlane16_swap_b32_e32 v57, v61
	v_permlane16_swap_b32_e32 v58, v62
	v_permlane16_swap_b32_e32 v59, v63
	v_permlane16_swap_b32_e32 v32, v36
	v_permlane16_swap_b32_e32 v33, v37
	v_permlane16_swap_b32_e32 v34, v38
	v_permlane16_swap_b32_e32 v35, v39
	v_permlane16_swap_b32_e32 v40, v44
	v_permlane16_swap_b32_e32 v41, v45
	v_permlane16_swap_b32_e32 v42, v46
	v_permlane16_swap_b32_e32 v43, v47
	v_permlane16_swap_b32_e32 v16, v20
	v_permlane16_swap_b32_e32 v17, v21
	v_permlane16_swap_b32_e32 v18, v22
	v_permlane16_swap_b32_e32 v19, v23
	v_permlane16_swap_b32_e32 v24, v28
	v_permlane16_swap_b32_e32 v25, v29
	v_permlane16_swap_b32_e32 v26, v30
	v_permlane16_swap_b32_e32 v27, v31
	v_permlane16_swap_b32_e32 v0, v4
	v_permlane16_swap_b32_e32 v1, v5
	v_permlane16_swap_b32_e32 v2, v6
	v_permlane16_swap_b32_e32 v3, v7
	v_permlane16_swap_b32_e32 v8, v12
	v_permlane16_swap_b32_e32 v9, v13
	v_permlane16_swap_b32_e32 v10, v14
	v_permlane16_swap_b32_e32 v11, v15
	v_permlane32_swap_b32_e32 v112, v116
	v_permlane32_swap_b32_e32 v113, v117
	v_permlane32_swap_b32_e32 v114, v118
	v_permlane32_swap_b32_e32 v115, v119
	v_permlane32_swap_b32_e32 v120, v124
	v_permlane32_swap_b32_e32 v121, v125
	v_permlane32_swap_b32_e32 v122, v126
	v_permlane32_swap_b32_e32 v123, v127
	v_permlane32_swap_b32_e32 v96, v100
	v_permlane32_swap_b32_e32 v97, v101
	v_permlane32_swap_b32_e32 v98, v102
	v_permlane32_swap_b32_e32 v99, v103
	v_permlane32_swap_b32_e32 v104, v108
	v_permlane32_swap_b32_e32 v105, v109
	v_permlane32_swap_b32_e32 v106, v110
	v_permlane32_swap_b32_e32 v107, v111
	v_permlane32_swap_b32_e32 v80, v84
	v_permlane32_swap_b32_e32 v81, v85
	v_permlane32_swap_b32_e32 v82, v86
	v_permlane32_swap_b32_e32 v83, v87
	v_permlane32_swap_b32_e32 v88, v92
	v_permlane32_swap_b32_e32 v89, v93
	v_permlane32_swap_b32_e32 v90, v94
	v_permlane32_swap_b32_e32 v91, v95
	v_permlane32_swap_b32_e32 v64, v68
	v_permlane32_swap_b32_e32 v65, v69
	v_permlane32_swap_b32_e32 v66, v70
	v_permlane32_swap_b32_e32 v67, v71
	v_permlane32_swap_b32_e32 v72, v76
	v_permlane32_swap_b32_e32 v73, v77
	v_permlane32_swap_b32_e32 v74, v78
	v_permlane32_swap_b32_e32 v75, v79
	v_permlane32_swap_b32_e32 v48, v52
	v_permlane32_swap_b32_e32 v49, v53
	v_permlane32_swap_b32_e32 v50, v54
	v_permlane32_swap_b32_e32 v51, v55
	v_permlane32_swap_b32_e32 v56, v60
	v_permlane32_swap_b32_e32 v57, v61
	v_permlane32_swap_b32_e32 v58, v62
	v_permlane32_swap_b32_e32 v59, v63
	v_permlane32_swap_b32_e32 v32, v36
	v_permlane32_swap_b32_e32 v33, v37
	v_permlane32_swap_b32_e32 v34, v38
	v_permlane32_swap_b32_e32 v35, v39
	v_permlane32_swap_b32_e32 v40, v44
	v_permlane32_swap_b32_e32 v41, v45
	v_permlane32_swap_b32_e32 v42, v46
	v_permlane32_swap_b32_e32 v43, v47
	v_permlane32_swap_b32_e32 v16, v20
	v_permlane32_swap_b32_e32 v17, v21
	v_permlane32_swap_b32_e32 v18, v22
	v_permlane32_swap_b32_e32 v19, v23
	v_permlane32_swap_b32_e32 v24, v28
	v_permlane32_swap_b32_e32 v25, v29
	v_permlane32_swap_b32_e32 v26, v30
	v_permlane32_swap_b32_e32 v27, v31
	v_permlane32_swap_b32_e32 v0, v4
	v_permlane32_swap_b32_e32 v1, v5
	v_permlane32_swap_b32_e32 v2, v6
	v_permlane32_swap_b32_e32 v3, v7
	v_permlane32_swap_b32_e32 v8, v12
	v_permlane32_swap_b32_e32 v9, v13
	v_permlane32_swap_b32_e32 v10, v14
	v_permlane32_swap_b32_e32 v11, v15
	s_nop 1
